# phase 7 tile epilogue: per-element reload of the x/out base pointer from the argument struct replaced by a 40-byte LDS table lookup, removing a dependent vector load and a vmcnt(0) drain per element
# speedup vs baseline: 1.0185x; 1.0112x over previous
; DI const float* xrow_ptr(const Params& p, int l, int row) {
;   if (l > 0) return p.out + (size_t)row * D;
;   return row < NP ? p.in[0] + (size_t)row * D : p.in[1] + (size_t)(row - NP) * D;
; }
; DI void phase7(const Params& p, int l, unsigned char* smem) {
;   const u16* MG = (const u16*)(p.ws + W_MG);
;   const float* mod = (const float*)(p.ws + W_MOD);
;   const int ntile = 32 + 128 * 8, nextra = (l + 1 < NL) ? WIN_TT + SMALLW_TT : 0;
;   for (int t0 = blockIdx.x; t0 < ntile + nextra; t0 += gridDim.x) {
.LBB0_997:
	s_or_b64 exec, exec, s[2:3]
	v_readlane_b32 s2, v254, 49
	s_barrier
	s_cmp_lt_i32 s2, 3
	s_movk_i32 s3, 0xf88
	s_cselect_b32 s87, s3, 0x420
	v_readlane_b32 s3, v254, 0
	s_cmp_ge_i32 s3, s87
	s_cbranch_scc1 .LBB0_1650
	s_ashr_i32 s3, s2, 31
	s_lshl_b64 s[6:7], s[2:3], 21
	s_cmp_lt_i32 s2, 1
	s_cselect_b64 s[20:21], -1, 0
	s_cmp_gt_i32 s2, 0
	s_cselect_b64 s[4:5], -1, 0
	s_and_b64 s[8:9], s[4:5], exec
	s_mul_i32 s94, s2, 10
	s_cselect_b32 s3, 0x120, 8
	s_add_i32 s8, s2, 1
	v_writelane_b32 v254, s3, 41
	s_add_i32 s3, s94, 2
	s_ashr_i32 s9, s8, 31
	v_writelane_b32 v254, s3, 39
	s_lshl_b64 s[12:13], s[8:9], 20
	s_lshl_b64 s[10:11], s[8:9], 17
	v_writelane_b32 v254, s12, 35
	v_writelane_b32 v255, s10, 9
	s_mul_hi_i32 s3, s8, 0x120000
	v_writelane_b32 v254, s13, 36
	v_writelane_b32 v255, s11, 10
	s_lshl_b64 s[10:11], s[8:9], 16
	s_lshl_b64 s[12:13], s[8:9], 19
	v_writelane_b32 v254, s3, 63
	s_mul_i32 s3, s8, 0x120000
	s_lshl_b64 s[56:57], s[8:9], 21
	s_mul_hi_i32 s16, s8, 0x2120000
	s_mul_i32 s51, s8, 0x2120000
	v_writelane_b32 v255, s3, 0
	s_mul_hi_i32 s3, s8, 0x90000
	s_mul_i32 s14, s8, 0x90000
	s_add_u32 s8, s76, 0x1c90000
	s_addc_u32 s9, s77, 0
	s_add_u32 s15, s8, s6
	v_writelane_b32 v255, s15, 5
	s_addc_u32 s15, s9, s7
	v_writelane_b32 v255, s15, 7
	s_add_i32 s15, s94, 3
	s_add_u32 s10, s76, s10
	s_addc_u32 s11, s77, s11
	s_add_u32 s18, s10, 0x2910000
	s_addc_u32 s19, s11, 0
	v_writelane_b32 v255, s18, 11
	s_add_u32 s10, s10, 0x28d0000
	s_addc_u32 s11, s11, 0
	v_writelane_b32 v255, s19, 12
	v_writelane_b32 v254, s15, 45
	v_writelane_b32 v255, s10, 13
	s_mul_i32 s2, s2, 3
	s_nop 0
	v_writelane_b32 v255, s11, 14
	v_readlane_b32 s10, v254, 54
	s_add_u32 s10, s10, s14
	s_nop 0
	v_writelane_b32 v255, s10, 1
	v_readlane_b32 s10, v254, 55
	s_addc_u32 s3, s10, s3
	v_writelane_b32 v255, s3, 2
	s_add_u32 s3, s76, 0x7b6b800
	v_writelane_b32 v254, s3, 54
	s_addc_u32 s3, s77, 0
	v_writelane_b32 v254, s3, 55
	s_add_u32 s3, s76, s6
	s_addc_u32 s6, s77, s7
	s_add_u32 s7, s3, 0x1c90100
	v_writelane_b32 v254, s7, 47
	s_addc_u32 s7, s6, 0
	s_add_u32 s10, s3, 0x1c90080
	v_writelane_b32 v254, s7, 50
	s_addc_u32 s11, s6, 0
	v_writelane_b32 v254, s10, 43
	s_add_u32 s6, s76, 0x9b6b780
	s_addc_u32 s7, s77, 0
	v_writelane_b32 v254, s11, 44
	v_writelane_b32 v254, s6, 56
	s_nop 1
	v_writelane_b32 v254, s7, 57
	s_nop 0
	v_readlane_b32 s3, v254, 52
	s_add_u32 s3, s3, s12
	s_nop 0
	v_writelane_b32 v254, s3, 52
	s_nop 0
	v_readlane_b32 s3, v254, 53
	s_addc_u32 s3, s3, s13
	s_nop 0
	v_writelane_b32 v254, s3, 53
	s_add_u32 s3, s8, s56
	v_writelane_b32 v254, s3, 58
	s_addc_u32 s3, s9, s57
	v_writelane_b32 v254, s3, 60
	s_add_u32 s42, s76, 0x1090000
	s_addc_u32 s17, s77, 0
	s_add_i32 s43, s2, 3
	v_readlane_b32 s93, v254, 26
	v_readlane_b32 s54, v254, 25
	v_readlane_b32 s55, v254, 24
	v_readlane_b32 s90, v254, 22
	v_readlane_b32 s91, v254, 20
	v_readlane_b32 s84, v254, 18
	v_readlane_b32 s85, v254, 17
	v_readlane_b32 s52, v254, 21
	v_readlane_b32 s53, v254, 16
	v_readlane_b32 s92, v254, 15
	v_readlane_b32 s80, v254, 14
	v_readlane_b32 s2, v254, 13
	v_readlane_b32 s81, v254, 19
	v_readlane_b32 s95, v254, 0
	v_writelane_b32 v254, s20, 61
	s_mov_b32 s86, s2
	s_nop 0
	v_writelane_b32 v254, s21, 62
	v_writelane_b32 v254, s17, 59
	s_load_dwordx2 s[2:3], s[0:1], 0x0
	v_mov_b32_e32 v242, 0x12110
	s_waitcnt lgkmcnt(0)
	v_mov_b64_e32 v[240:241], s[2:3]
	s_load_dwordx2 s[2:3], s[0:1], 0x8
	ds_write_b64 v242, v[240:241]
	s_waitcnt lgkmcnt(0)
	v_mov_b64_e32 v[244:245], s[2:3]
	s_load_dwordx2 s[2:3], s[0:1], 0x120
	ds_write_b64 v242, v[244:245] offset:8
	s_waitcnt lgkmcnt(0)
	v_mov_b64_e32 v[246:247], s[2:3]
	s_nop 0
	ds_write_b64 v242, v[246:247] offset:32
	s_waitcnt lgkmcnt(0)
	s_branch .LBB0_1000

; DI const float* xrow_ptr(const Params& p, int l, int row) {
;   if (l > 0) return p.out + (size_t)row * D;
;   return row < NP ? p.in[0] + (size_t)row * D : p.in[1] + (size_t)(row - NP) * D;
; }
; DI void phase7(const Params& p, int l, unsigned char* smem) {
;     ...
;     foreach_acc(acc, m0, n0, [&](int row, int col, float v) {
;       float xo = xrow_ptr(p, l, row)[col];
;       float gt = mod[(l * 10 + bidx_of(row)) * 3072 + 2048 + col];
;       p.out[(size_t)row * D + col] = xo + gt * v;
;     });
.LBB0_1013:
	v_subrev_u32_e32 v72, s0, v72
	v_and_or_b32 v72, v72, 40, v242
	ds_read_b64 v[72:73], v72
	v_and_b32_e32 v65, 64, v65
	v_and_b32_e32 v64, 31, v64
	v_or3_b32 v162, v64, v65, s46
	v_lshlrev_b64 v[70:71], 12, v[70:71]
	v_lshlrev_b64 v[74:75], 2, v[162:163]
	v_cmp_gt_i32_e32 vcc, s50, v66
	v_ashrrev_i32_e32 v121, 13, v122
	v_add_u32_e32 v120, 0x800, v162
	v_readlane_b32 s2, v254, 37
	v_readlane_b32 s3, v254, 38
	v_lshlrev_b64 v[68:69], 12, v[68:69]
	v_or_b32_e32 v124, 1, v123
	v_lshl_add_u64 v[64:65], s[2:3], 0, v[74:75]
	v_lshl_add_u64 v[68:69], v[64:65], 0, v[68:69]
	v_cmp_lt_i32_e64 s[8:9], s64, v66
	s_mov_b64 s[2:3], -1
	s_waitcnt lgkmcnt(0)
	v_lshl_add_u64 v[70:71], v[72:73], 0, v[70:71]
	v_lshl_add_u64 v[70:71], v[70:71], 0, v[74:75]
	v_add_u32_e32 v72, 0xffffc000, v66
	global_load_dword v73, v[70:71], off
	v_lshrrev_b32_e32 v70, 4, v72
	v_or_b32_e32 v70, 2, v70
	v_cndmask_b32_e32 v70, v70, v121, vcc
	v_add_u32_e32 v70, s94, v70
	v_mul_lo_u32 v81, v70, s74
	v_add_u32_e32 v70, v81, v120
	v_ashrrev_i32_e32 v71, 31, v70
	v_lshl_add_u64 v[70:71], v[70:71], 2, s[78:79]
	global_load_dword v70, v[70:71], off
	s_andn2_b64 vcc, exec, s[20:21]
	s_waitcnt vmcnt(0)
	v_fmac_f32_e32 v73, v48, v70
	global_store_dword v[68:69], v73, off
	v_or_b32_e32 v68, v122, v124
	v_cndmask_b32_e64 v48, 0, 1, s[20:21]
	v_cmp_ne_u32_e64 s[6:7], 1, v48
	v_cmp_lt_i32_e64 s[10:11], s64, v68
	s_cbranch_vccnz .LBB0_1019
	s_and_saveexec_b64 s[2:3], s[10:11]
	s_xor_b64 s[2:3], exec, s[2:3]
	v_mov_b32_e32 v69, v163
	v_add_u32_e32 v74, 0xffffc000, v68
	v_mov_b32_e32 v75, v163
	v_mov_b64_e32 v[70:71], v[68:69]
	s_or_saveexec_b64 s[2:3], s[2:3]
	v_readlane_b32 s10, v254, 2
	v_readlane_b32 s11, v254, 3
	s_nop 1
	v_mov_b64_e32 v[76:77], s[10:11]
	s_xor_b64 exec, exec, s[2:3]
	v_ashrrev_i32_e32 v69, 31, v68
	v_mov_b64_e32 v[76:77], s[0:1]
	v_mov_b64_e32 v[74:75], v[68:69]
	v_mov_b64_e32 v[70:71], v[68:69]
	s_or_b64 exec, exec, s[2:3]
	s_mov_b64 s[2:3], 0

; DI const float* xrow_ptr(const Params& p, int l, int row) {
;   if (l > 0) return p.out + (size_t)row * D;
;   return row < NP ? p.in[0] + (size_t)row * D : p.in[1] + (size_t)(row - NP) * D;
; }
; DI void phase7(const Params& p, int l, unsigned char* smem) {
;     ...
;     foreach_acc(acc, m0, n0, [&](int row, int col, float v) {
;       float xo = xrow_ptr(p, l, row)[col];
;       float gt = mod[(l * 10 + bidx_of(row)) * 3072 + 2048 + col];
;       p.out[(size_t)row * D + col] = xo + gt * v;
;     });
.LBB0_1021:
	v_subrev_u32_e32 v76, s0, v76
	v_and_or_b32 v76, v76, 40, v242
	ds_read_b64 v[76:77], v76
	v_lshlrev_b64 v[74:75], 12, v[74:75]
	v_cmp_gt_i32_e32 vcc, s50, v68
	v_or_b32_e32 v125, 2, v123
	v_cmp_lt_i32_e64 s[10:11], s64, v68
	s_mov_b64 s[2:3], -1
	s_waitcnt lgkmcnt(0)
	v_lshl_add_u64 v[74:75], v[76:77], 0, v[74:75]
	v_add_u32_e32 v76, 0xffffc000, v68
	v_lshrrev_b32_e32 v48, 4, v76
	v_or_b32_e32 v48, 2, v48
	v_cndmask_b32_e32 v48, v48, v121, vcc
	v_add_u32_e32 v48, s94, v48
	v_lshl_add_u64 v[74:75], v[162:163], 2, v[74:75]
	v_mul_lo_u32 v87, v48, s74
	global_load_dword v73, v[74:75], off
	v_add_u32_e32 v74, v87, v120
	v_ashrrev_i32_e32 v75, 31, v74
	v_lshl_add_u64 v[74:75], v[74:75], 2, s[78:79]
	global_load_dword v48, v[74:75], off
	s_and_b64 vcc, exec, s[6:7]
	s_waitcnt vmcnt(0)
	v_fmac_f32_e32 v73, v49, v48
	v_lshlrev_b64 v[48:49], 12, v[70:71]
	v_lshl_add_u64 v[48:49], v[64:65], 0, v[48:49]
	global_store_dword v[48:49], v73, off
	v_or_b32_e32 v48, v122, v125
	v_cmp_lt_i32_e64 s[12:13], s64, v48
	s_cbranch_vccnz .LBB0_1027
	s_and_saveexec_b64 s[2:3], s[12:13]
	s_xor_b64 s[2:3], exec, s[2:3]
	v_mov_b32_e32 v49, v163
	v_add_u32_e32 v74, 0xffffc000, v48
	v_mov_b32_e32 v75, v163
	v_mov_b64_e32 v[70:71], v[48:49]
	s_or_saveexec_b64 s[2:3], s[2:3]
	v_readlane_b32 s12, v254, 2
	v_readlane_b32 s13, v254, 3
	s_nop 1
	v_mov_b64_e32 v[78:79], s[12:13]
	s_xor_b64 exec, exec, s[2:3]
	v_ashrrev_i32_e32 v49, 31, v48
	v_mov_b64_e32 v[78:79], s[0:1]
	v_mov_b64_e32 v[74:75], v[48:49]
	v_mov_b64_e32 v[70:71], v[48:49]
	s_or_b64 exec, exec, s[2:3]
	s_mov_b64 s[2:3], 0

; DI const float* xrow_ptr(const Params& p, int l, int row) {
;   if (l > 0) return p.out + (size_t)row * D;
;   return row < NP ? p.in[0] + (size_t)row * D : p.in[1] + (size_t)(row - NP) * D;
; }
; DI void phase7(const Params& p, int l, unsigned char* smem) {
;     ...
;     foreach_acc(acc, m0, n0, [&](int row, int col, float v) {
;       float xo = xrow_ptr(p, l, row)[col];
;       float gt = mod[(l * 10 + bidx_of(row)) * 3072 + 2048 + col];
;       p.out[(size_t)row * D + col] = xo + gt * v;
;     });
.LBB0_1029:
	v_subrev_u32_e32 v78, s0, v78
	v_and_or_b32 v78, v78, 40, v242
	ds_read_b64 v[78:79], v78
	v_lshlrev_b64 v[74:75], 12, v[74:75]
	v_add_u32_e32 v80, 0xffffc000, v48
	v_cmp_gt_i32_e32 vcc, s50, v48
	v_lshlrev_b64 v[70:71], 12, v[70:71]
	v_lshl_add_u64 v[70:71], v[64:65], 0, v[70:71]
	v_or_b32_e32 v126, 3, v123
	v_cmp_lt_i32_e64 s[12:13], s64, v48
	s_mov_b64 s[2:3], -1
	s_waitcnt lgkmcnt(0)
	v_lshl_add_u64 v[74:75], v[78:79], 0, v[74:75]
	v_lshl_add_u64 v[74:75], v[162:163], 2, v[74:75]
	global_load_dword v73, v[74:75], off
	v_lshrrev_b32_e32 v74, 4, v80
	v_or_b32_e32 v74, 2, v74
	v_cndmask_b32_e32 v74, v74, v121, vcc
	v_add_u32_e32 v74, s94, v74
	v_mul_lo_u32 v93, v74, s74
	v_add_u32_e32 v74, v93, v120
	v_ashrrev_i32_e32 v75, 31, v74
	v_lshl_add_u64 v[74:75], v[74:75], 2, s[78:79]
	global_load_dword v74, v[74:75], off
	s_and_b64 vcc, exec, s[6:7]
	s_waitcnt vmcnt(0)
	v_fmac_f32_e32 v73, v50, v74
	global_store_dword v[70:71], v73, off
	v_or_b32_e32 v70, v122, v126
	v_cmp_lt_i32_e64 s[14:15], s64, v70
	s_cbranch_vccnz .LBB0_1035
	s_and_saveexec_b64 s[2:3], s[14:15]
	s_xor_b64 s[2:3], exec, s[2:3]
	v_mov_b32_e32 v71, v163
	v_add_u32_e32 v78, 0xffffc000, v70
	v_mov_b32_e32 v79, v163
	v_mov_b64_e32 v[74:75], v[70:71]
	s_or_saveexec_b64 s[2:3], s[2:3]
	v_readlane_b32 s14, v254, 2
	v_readlane_b32 s15, v254, 3
	s_nop 1
	v_mov_b64_e32 v[82:83], s[14:15]
	s_xor_b64 exec, exec, s[2:3]
	v_ashrrev_i32_e32 v71, 31, v70
	v_mov_b64_e32 v[82:83], s[0:1]
	v_mov_b64_e32 v[78:79], v[70:71]
	v_mov_b64_e32 v[74:75], v[70:71]
	s_or_b64 exec, exec, s[2:3]
	s_mov_b64 s[2:3], 0

; DI const float* xrow_ptr(const Params& p, int l, int row) {
;   if (l > 0) return p.out + (size_t)row * D;
;   return row < NP ? p.in[0] + (size_t)row * D : p.in[1] + (size_t)(row - NP) * D;
; }
; DI void phase7(const Params& p, int l, unsigned char* smem) {
;     ...
;     foreach_acc(acc, m0, n0, [&](int row, int col, float v) {
;       float xo = xrow_ptr(p, l, row)[col];
;       float gt = mod[(l * 10 + bidx_of(row)) * 3072 + 2048 + col];
;       p.out[(size_t)row * D + col] = xo + gt * v;
;     });
.LBB0_1037:
	v_subrev_u32_e32 v82, s0, v82
	v_and_or_b32 v82, v82, 40, v242
	ds_read_b64 v[82:83], v82
	v_lshlrev_b64 v[78:79], 12, v[78:79]
	v_cmp_gt_i32_e32 vcc, s50, v70
	v_or_b32_e32 v127, 8, v123
	v_cmp_lt_i32_e64 s[14:15], s64, v70
	s_mov_b64 s[2:3], -1
	s_waitcnt lgkmcnt(0)
	v_lshl_add_u64 v[78:79], v[82:83], 0, v[78:79]
	v_add_u32_e32 v82, 0xffffc000, v70
	v_lshrrev_b32_e32 v50, 4, v82
	v_or_b32_e32 v50, 2, v50
	v_cndmask_b32_e32 v50, v50, v121, vcc
	v_add_u32_e32 v50, s94, v50
	v_lshl_add_u64 v[78:79], v[162:163], 2, v[78:79]
	v_mul_lo_u32 v99, v50, s74
	global_load_dword v73, v[78:79], off
	v_add_u32_e32 v78, v99, v120
	v_ashrrev_i32_e32 v79, 31, v78
	v_lshl_add_u64 v[78:79], v[78:79], 2, s[78:79]
	global_load_dword v50, v[78:79], off
	s_and_b64 vcc, exec, s[6:7]
	s_waitcnt vmcnt(0)
	v_fmac_f32_e32 v73, v51, v50
	v_lshlrev_b64 v[50:51], 12, v[74:75]
	v_lshl_add_u64 v[50:51], v[64:65], 0, v[50:51]
	global_store_dword v[50:51], v73, off
	v_or_b32_e32 v50, v122, v127
	v_cmp_lt_i32_e64 s[16:17], s64, v50
	s_cbranch_vccnz .LBB0_1043
	s_and_saveexec_b64 s[2:3], s[16:17]
	s_xor_b64 s[2:3], exec, s[2:3]
	v_mov_b32_e32 v51, v163
	v_add_u32_e32 v78, 0xffffc000, v50
	v_mov_b32_e32 v79, v163
	v_mov_b64_e32 v[74:75], v[50:51]
	s_or_saveexec_b64 s[2:3], s[2:3]
	v_readlane_b32 s16, v254, 2
	v_readlane_b32 s17, v254, 3
	s_nop 1
	v_mov_b64_e32 v[84:85], s[16:17]
	s_xor_b64 exec, exec, s[2:3]
	v_ashrrev_i32_e32 v51, 31, v50
	v_mov_b64_e32 v[84:85], s[0:1]
	v_mov_b64_e32 v[78:79], v[50:51]
	v_mov_b64_e32 v[74:75], v[50:51]
	s_or_b64 exec, exec, s[2:3]
	s_mov_b64 s[2:3], 0

; DI const float* xrow_ptr(const Params& p, int l, int row) {
;   if (l > 0) return p.out + (size_t)row * D;
;   return row < NP ? p.in[0] + (size_t)row * D : p.in[1] + (size_t)(row - NP) * D;
; }
; DI void phase7(const Params& p, int l, unsigned char* smem) {
;     ...
;     foreach_acc(acc, m0, n0, [&](int row, int col, float v) {
;       float xo = xrow_ptr(p, l, row)[col];
;       float gt = mod[(l * 10 + bidx_of(row)) * 3072 + 2048 + col];
;       p.out[(size_t)row * D + col] = xo + gt * v;
;     });
.LBB0_1045:
	v_subrev_u32_e32 v84, s0, v84
	v_and_or_b32 v84, v84, 40, v242
	ds_read_b64 v[84:85], v84
	v_add_u32_e32 v86, 0xffffc000, v50
	v_lshrrev_b32_e32 v77, 4, v86
	v_cmp_gt_i32_e32 vcc, s50, v50
	v_or_b32_e32 v77, 2, v77
	v_lshlrev_b64 v[78:79], 12, v[78:79]
	v_cndmask_b32_e32 v77, v77, v121, vcc
	v_add_u32_e32 v77, s94, v77
	v_mul_lo_u32 v105, v77, s74
	v_lshlrev_b64 v[74:75], 12, v[74:75]
	v_lshl_add_u64 v[74:75], v[64:65], 0, v[74:75]
	v_or_b32_e32 v128, 9, v123
	v_cmp_lt_i32_e64 s[16:17], s64, v50
	s_mov_b64 s[2:3], -1
	s_and_b64 vcc, exec, s[6:7]
	s_waitcnt lgkmcnt(0)
	v_lshl_add_u64 v[78:79], v[84:85], 0, v[78:79]
	v_lshl_add_u64 v[78:79], v[162:163], 2, v[78:79]
	global_load_dword v73, v[78:79], off
	v_add_u32_e32 v78, v105, v120
	v_ashrrev_i32_e32 v79, 31, v78
	v_lshl_add_u64 v[78:79], v[78:79], 2, s[78:79]
	global_load_dword v77, v[78:79], off
	s_waitcnt vmcnt(0)
	v_fmac_f32_e32 v73, v52, v77
	global_store_dword v[74:75], v73, off
	v_or_b32_e32 v74, v122, v128
	v_cmp_lt_i32_e64 s[18:19], s64, v74
	s_cbranch_vccnz .LBB0_1051
	s_and_saveexec_b64 s[2:3], s[18:19]
	s_xor_b64 s[2:3], exec, s[2:3]
	v_mov_b32_e32 v75, v163
	v_add_u32_e32 v84, 0xffffc000, v74
	v_mov_b32_e32 v85, v163
	v_mov_b64_e32 v[78:79], v[74:75]
	s_or_saveexec_b64 s[2:3], s[2:3]
	v_readlane_b32 s18, v254, 2
	v_readlane_b32 s19, v254, 3
	s_nop 1
	v_mov_b64_e32 v[88:89], s[18:19]
	s_xor_b64 exec, exec, s[2:3]
	v_ashrrev_i32_e32 v75, 31, v74
	v_mov_b64_e32 v[88:89], s[0:1]
	v_mov_b64_e32 v[84:85], v[74:75]
	v_mov_b64_e32 v[78:79], v[74:75]
	s_or_b64 exec, exec, s[2:3]
	s_mov_b64 s[2:3], 0

; DI const float* xrow_ptr(const Params& p, int l, int row) {
;   if (l > 0) return p.out + (size_t)row * D;
;   return row < NP ? p.in[0] + (size_t)row * D : p.in[1] + (size_t)(row - NP) * D;
; }
; DI void phase7(const Params& p, int l, unsigned char* smem) {
;     ...
;     foreach_acc(acc, m0, n0, [&](int row, int col, float v) {
;       float xo = xrow_ptr(p, l, row)[col];
;       float gt = mod[(l * 10 + bidx_of(row)) * 3072 + 2048 + col];
;       p.out[(size_t)row * D + col] = xo + gt * v;
;     });
.LBB0_1053:
	v_subrev_u32_e32 v88, s0, v88
	v_and_or_b32 v88, v88, 40, v242
	ds_read_b64 v[88:89], v88
	v_lshlrev_b64 v[84:85], 12, v[84:85]
	v_cmp_gt_i32_e32 vcc, s50, v74
	v_or_b32_e32 v129, 10, v123
	v_cmp_lt_i32_e64 s[18:19], s64, v74
	s_mov_b64 s[2:3], -1
	s_waitcnt lgkmcnt(0)
	v_lshl_add_u64 v[84:85], v[88:89], 0, v[84:85]
	v_add_u32_e32 v88, 0xffffc000, v74
	v_lshrrev_b32_e32 v52, 4, v88
	v_or_b32_e32 v52, 2, v52
	v_cndmask_b32_e32 v52, v52, v121, vcc
	v_add_u32_e32 v52, s94, v52
	v_lshl_add_u64 v[84:85], v[162:163], 2, v[84:85]
	v_mul_lo_u32 v139, v52, s74
	global_load_dword v73, v[84:85], off
	v_add_u32_e32 v84, v139, v120
	v_ashrrev_i32_e32 v85, 31, v84
	v_lshl_add_u64 v[84:85], v[84:85], 2, s[78:79]
	global_load_dword v52, v[84:85], off
	s_and_b64 vcc, exec, s[6:7]
	s_waitcnt vmcnt(0)
	v_fmac_f32_e32 v73, v53, v52
	v_lshlrev_b64 v[52:53], 12, v[78:79]
	v_lshl_add_u64 v[52:53], v[64:65], 0, v[52:53]
	global_store_dword v[52:53], v73, off
	v_or_b32_e32 v52, v122, v129
	v_cmp_lt_i32_e64 s[20:21], s64, v52
	s_cbranch_vccnz .LBB0_1059
	s_and_saveexec_b64 s[2:3], s[20:21]
	s_xor_b64 s[2:3], exec, s[2:3]
	v_mov_b32_e32 v53, v163
	v_add_u32_e32 v84, 0xffffc000, v52
	v_mov_b32_e32 v85, v163
	v_mov_b64_e32 v[78:79], v[52:53]
	s_or_saveexec_b64 s[2:3], s[2:3]
	v_readlane_b32 s20, v254, 2
	v_readlane_b32 s21, v254, 3
	s_nop 1
	v_mov_b64_e32 v[90:91], s[20:21]
	s_xor_b64 exec, exec, s[2:3]
	v_ashrrev_i32_e32 v53, 31, v52
	v_mov_b64_e32 v[90:91], s[0:1]
	v_mov_b64_e32 v[84:85], v[52:53]
	v_mov_b64_e32 v[78:79], v[52:53]
	s_or_b64 exec, exec, s[2:3]
	s_mov_b64 s[2:3], 0

; DI const float* xrow_ptr(const Params& p, int l, int row) {
;   if (l > 0) return p.out + (size_t)row * D;
;   return row < NP ? p.in[0] + (size_t)row * D : p.in[1] + (size_t)(row - NP) * D;
; }
; DI void phase7(const Params& p, int l, unsigned char* smem) {
;     ...
;     foreach_acc(acc, m0, n0, [&](int row, int col, float v) {
;       float xo = xrow_ptr(p, l, row)[col];
;       float gt = mod[(l * 10 + bidx_of(row)) * 3072 + 2048 + col];
;       p.out[(size_t)row * D + col] = xo + gt * v;
;     });
.LBB0_1061:
	v_subrev_u32_e32 v90, s0, v90
	v_and_or_b32 v90, v90, 40, v242
	ds_read_b64 v[90:91], v90
	v_add_u32_e32 v92, 0xffffc000, v52
	v_lshrrev_b32_e32 v77, 4, v92
	v_cmp_gt_i32_e32 vcc, s50, v52
	v_or_b32_e32 v77, 2, v77
	v_lshlrev_b64 v[84:85], 12, v[84:85]
	v_cndmask_b32_e32 v77, v77, v121, vcc
	v_add_u32_e32 v77, s94, v77
	v_mul_lo_u32 v140, v77, s74
	v_lshlrev_b64 v[78:79], 12, v[78:79]
	v_lshl_add_u64 v[78:79], v[64:65], 0, v[78:79]
	v_or_b32_e32 v130, 11, v123
	v_cmp_lt_i32_e64 s[20:21], s64, v52
	s_mov_b64 s[2:3], -1
	s_and_b64 vcc, exec, s[6:7]
	s_waitcnt lgkmcnt(0)
	v_lshl_add_u64 v[84:85], v[90:91], 0, v[84:85]
	v_lshl_add_u64 v[84:85], v[162:163], 2, v[84:85]
	global_load_dword v73, v[84:85], off
	v_add_u32_e32 v84, v140, v120
	v_ashrrev_i32_e32 v85, 31, v84
	v_lshl_add_u64 v[84:85], v[84:85], 2, s[78:79]
	global_load_dword v77, v[84:85], off
	s_waitcnt vmcnt(0)
	v_fmac_f32_e32 v73, v54, v77
	global_store_dword v[78:79], v73, off
	v_or_b32_e32 v78, v122, v130
	v_cmp_lt_i32_e64 s[22:23], s64, v78
	s_cbranch_vccnz .LBB0_1067
	s_and_saveexec_b64 s[2:3], s[22:23]
	s_xor_b64 s[2:3], exec, s[2:3]
	v_mov_b32_e32 v79, v163
	v_add_u32_e32 v90, 0xffffc000, v78
	v_mov_b32_e32 v91, v163
	v_mov_b64_e32 v[84:85], v[78:79]
	s_or_saveexec_b64 s[2:3], s[2:3]
	v_readlane_b32 s22, v254, 2
	v_readlane_b32 s23, v254, 3
	s_nop 1
	v_mov_b64_e32 v[94:95], s[22:23]
	s_xor_b64 exec, exec, s[2:3]
	v_ashrrev_i32_e32 v79, 31, v78
	v_mov_b64_e32 v[94:95], s[0:1]
	v_mov_b64_e32 v[90:91], v[78:79]
	v_mov_b64_e32 v[84:85], v[78:79]
	s_or_b64 exec, exec, s[2:3]
	s_mov_b64 s[2:3], 0

; DI const float* xrow_ptr(const Params& p, int l, int row) {
;   if (l > 0) return p.out + (size_t)row * D;
;   return row < NP ? p.in[0] + (size_t)row * D : p.in[1] + (size_t)(row - NP) * D;
; }
; DI void phase7(const Params& p, int l, unsigned char* smem) {
;     ...
;     foreach_acc(acc, m0, n0, [&](int row, int col, float v) {
;       float xo = xrow_ptr(p, l, row)[col];
;       float gt = mod[(l * 10 + bidx_of(row)) * 3072 + 2048 + col];
;       p.out[(size_t)row * D + col] = xo + gt * v;
;     });
.LBB0_1069:
	v_subrev_u32_e32 v94, s0, v94
	v_and_or_b32 v94, v94, 40, v242
	ds_read_b64 v[94:95], v94
	v_lshlrev_b64 v[90:91], 12, v[90:91]
	v_cmp_gt_i32_e32 vcc, s50, v78
	v_or_b32_e32 v131, 16, v123
	v_cmp_lt_i32_e64 s[22:23], s64, v78
	s_mov_b64 s[2:3], -1
	s_waitcnt lgkmcnt(0)
	v_lshl_add_u64 v[90:91], v[94:95], 0, v[90:91]
	v_add_u32_e32 v94, 0xffffc000, v78
	v_lshrrev_b32_e32 v54, 4, v94
	v_or_b32_e32 v54, 2, v54
	v_cndmask_b32_e32 v54, v54, v121, vcc
	v_add_u32_e32 v54, s94, v54
	v_lshl_add_u64 v[90:91], v[162:163], 2, v[90:91]
	v_mul_lo_u32 v141, v54, s74
	global_load_dword v73, v[90:91], off
	v_add_u32_e32 v90, v141, v120
	v_ashrrev_i32_e32 v91, 31, v90
	v_lshl_add_u64 v[90:91], v[90:91], 2, s[78:79]
	global_load_dword v54, v[90:91], off
	s_and_b64 vcc, exec, s[6:7]
	s_waitcnt vmcnt(0)
	v_fmac_f32_e32 v73, v55, v54
	v_lshlrev_b64 v[54:55], 12, v[84:85]
	v_lshl_add_u64 v[54:55], v[64:65], 0, v[54:55]
	global_store_dword v[54:55], v73, off
	v_or_b32_e32 v54, v122, v131
	v_cmp_lt_i32_e64 s[24:25], s64, v54
	s_cbranch_vccnz .LBB0_1075
	s_and_saveexec_b64 s[2:3], s[24:25]
	s_xor_b64 s[2:3], exec, s[2:3]
	v_mov_b32_e32 v55, v163
	v_add_u32_e32 v90, 0xffffc000, v54
	v_mov_b32_e32 v91, v163
	v_mov_b64_e32 v[84:85], v[54:55]
	s_or_saveexec_b64 s[2:3], s[2:3]
	v_readlane_b32 s24, v254, 2
	v_readlane_b32 s25, v254, 3
	s_nop 1
	v_mov_b64_e32 v[96:97], s[24:25]
	s_xor_b64 exec, exec, s[2:3]
	v_ashrrev_i32_e32 v55, 31, v54
	v_mov_b64_e32 v[96:97], s[0:1]
	v_mov_b64_e32 v[90:91], v[54:55]
	v_mov_b64_e32 v[84:85], v[54:55]
	s_or_b64 exec, exec, s[2:3]
	s_mov_b64 s[2:3], 0

; DI const float* xrow_ptr(const Params& p, int l, int row) {
;   if (l > 0) return p.out + (size_t)row * D;
;   return row < NP ? p.in[0] + (size_t)row * D : p.in[1] + (size_t)(row - NP) * D;
; }
; DI void phase7(const Params& p, int l, unsigned char* smem) {
;     ...
;     foreach_acc(acc, m0, n0, [&](int row, int col, float v) {
;       float xo = xrow_ptr(p, l, row)[col];
;       float gt = mod[(l * 10 + bidx_of(row)) * 3072 + 2048 + col];
;       p.out[(size_t)row * D + col] = xo + gt * v;
;     });
.LBB0_1077:
	v_subrev_u32_e32 v96, s0, v96
	v_and_or_b32 v96, v96, 40, v242
	ds_read_b64 v[96:97], v96
	v_add_u32_e32 v98, 0xffffc000, v54
	v_lshrrev_b32_e32 v77, 4, v98
	v_cmp_gt_i32_e32 vcc, s50, v54
	v_or_b32_e32 v77, 2, v77
	v_lshlrev_b64 v[90:91], 12, v[90:91]
	v_cndmask_b32_e32 v77, v77, v121, vcc
	v_add_u32_e32 v77, s94, v77
	v_mul_lo_u32 v142, v77, s74
	v_lshlrev_b64 v[84:85], 12, v[84:85]
	v_lshl_add_u64 v[84:85], v[64:65], 0, v[84:85]
	v_or_b32_e32 v132, 17, v123
	v_cmp_lt_i32_e64 s[24:25], s64, v54
	s_mov_b64 s[2:3], -1
	s_and_b64 vcc, exec, s[6:7]
	s_waitcnt lgkmcnt(0)
	v_lshl_add_u64 v[90:91], v[96:97], 0, v[90:91]
	v_lshl_add_u64 v[90:91], v[162:163], 2, v[90:91]
	global_load_dword v73, v[90:91], off
	v_add_u32_e32 v90, v142, v120
	v_ashrrev_i32_e32 v91, 31, v90
	v_lshl_add_u64 v[90:91], v[90:91], 2, s[78:79]
	global_load_dword v77, v[90:91], off
	s_waitcnt vmcnt(0)
	v_fmac_f32_e32 v73, v56, v77
	global_store_dword v[84:85], v73, off
	v_or_b32_e32 v84, v122, v132
	v_cmp_lt_i32_e64 s[26:27], s64, v84
	s_cbranch_vccnz .LBB0_1083
	s_and_saveexec_b64 s[2:3], s[26:27]
	s_xor_b64 s[2:3], exec, s[2:3]
	v_mov_b32_e32 v85, v163
	v_add_u32_e32 v96, 0xffffc000, v84
	v_mov_b32_e32 v97, v163
	v_mov_b64_e32 v[90:91], v[84:85]
	s_or_saveexec_b64 s[2:3], s[2:3]
	v_readlane_b32 s26, v254, 2
	v_readlane_b32 s27, v254, 3
	s_nop 1
	v_mov_b64_e32 v[100:101], s[26:27]
	s_xor_b64 exec, exec, s[2:3]
	v_ashrrev_i32_e32 v85, 31, v84
	v_mov_b64_e32 v[100:101], s[0:1]
	v_mov_b64_e32 v[96:97], v[84:85]
	v_mov_b64_e32 v[90:91], v[84:85]
	s_or_b64 exec, exec, s[2:3]
	s_mov_b64 s[2:3], 0

; DI const float* xrow_ptr(const Params& p, int l, int row) {
;   if (l > 0) return p.out + (size_t)row * D;
;   return row < NP ? p.in[0] + (size_t)row * D : p.in[1] + (size_t)(row - NP) * D;
; }
; DI void phase7(const Params& p, int l, unsigned char* smem) {
;     ...
;     foreach_acc(acc, m0, n0, [&](int row, int col, float v) {
;       float xo = xrow_ptr(p, l, row)[col];
;       float gt = mod[(l * 10 + bidx_of(row)) * 3072 + 2048 + col];
;       p.out[(size_t)row * D + col] = xo + gt * v;
;     });
.LBB0_1085:
	v_subrev_u32_e32 v100, s0, v100
	v_and_or_b32 v100, v100, 40, v242
	ds_read_b64 v[100:101], v100
	v_lshlrev_b64 v[96:97], 12, v[96:97]
	v_cmp_gt_i32_e32 vcc, s50, v84
	v_or_b32_e32 v133, 18, v123
	v_cmp_lt_i32_e64 s[26:27], s64, v84
	s_mov_b64 s[2:3], -1
	s_waitcnt lgkmcnt(0)
	v_lshl_add_u64 v[96:97], v[100:101], 0, v[96:97]
	v_add_u32_e32 v100, 0xffffc000, v84
	v_lshrrev_b32_e32 v56, 4, v100
	v_or_b32_e32 v56, 2, v56
	v_cndmask_b32_e32 v56, v56, v121, vcc
	v_add_u32_e32 v56, s94, v56
	v_lshl_add_u64 v[96:97], v[162:163], 2, v[96:97]
	v_mul_lo_u32 v143, v56, s74
	global_load_dword v73, v[96:97], off
	v_add_u32_e32 v96, v143, v120
	v_ashrrev_i32_e32 v97, 31, v96
	v_lshl_add_u64 v[96:97], v[96:97], 2, s[78:79]
	global_load_dword v56, v[96:97], off
	s_and_b64 vcc, exec, s[6:7]
	s_waitcnt vmcnt(0)
	v_fmac_f32_e32 v73, v57, v56
	v_lshlrev_b64 v[56:57], 12, v[90:91]
	v_lshl_add_u64 v[56:57], v[64:65], 0, v[56:57]
	global_store_dword v[56:57], v73, off
	v_or_b32_e32 v56, v122, v133
	v_cmp_lt_i32_e64 s[28:29], s64, v56
	s_cbranch_vccnz .LBB0_1091
	s_and_saveexec_b64 s[2:3], s[28:29]
	s_xor_b64 s[2:3], exec, s[2:3]
	v_mov_b32_e32 v57, v163
	v_add_u32_e32 v96, 0xffffc000, v56
	v_mov_b32_e32 v97, v163
	v_mov_b64_e32 v[90:91], v[56:57]
	s_or_saveexec_b64 s[2:3], s[2:3]
	v_readlane_b32 s28, v254, 2
	v_readlane_b32 s29, v254, 3
	s_nop 1
	v_mov_b64_e32 v[102:103], s[28:29]
	s_xor_b64 exec, exec, s[2:3]
	v_ashrrev_i32_e32 v57, 31, v56
	v_mov_b64_e32 v[102:103], s[0:1]
	v_mov_b64_e32 v[96:97], v[56:57]
	v_mov_b64_e32 v[90:91], v[56:57]
	s_or_b64 exec, exec, s[2:3]
	s_mov_b64 s[2:3], 0

; DI const float* xrow_ptr(const Params& p, int l, int row) {
;   if (l > 0) return p.out + (size_t)row * D;
;   return row < NP ? p.in[0] + (size_t)row * D : p.in[1] + (size_t)(row - NP) * D;
; }
; DI void phase7(const Params& p, int l, unsigned char* smem) {
;     ...
;     foreach_acc(acc, m0, n0, [&](int row, int col, float v) {
;       float xo = xrow_ptr(p, l, row)[col];
;       float gt = mod[(l * 10 + bidx_of(row)) * 3072 + 2048 + col];
;       p.out[(size_t)row * D + col] = xo + gt * v;
;     });
.LBB0_1093:
	v_subrev_u32_e32 v102, s0, v102
	v_and_or_b32 v102, v102, 40, v242
	ds_read_b64 v[102:103], v102
	v_add_u32_e32 v104, 0xffffc000, v56
	v_lshrrev_b32_e32 v77, 4, v104
	v_cmp_gt_i32_e32 vcc, s50, v56
	v_or_b32_e32 v77, 2, v77
	v_lshlrev_b64 v[96:97], 12, v[96:97]
	v_cndmask_b32_e32 v77, v77, v121, vcc
	v_add_u32_e32 v77, s94, v77
	v_mul_lo_u32 v144, v77, s74
	v_lshlrev_b64 v[90:91], 12, v[90:91]
	v_lshl_add_u64 v[90:91], v[64:65], 0, v[90:91]
	v_or_b32_e32 v134, 19, v123
	v_cmp_lt_i32_e64 s[28:29], s64, v56
	s_mov_b64 s[2:3], -1
	s_and_b64 vcc, exec, s[6:7]
	s_waitcnt lgkmcnt(0)
	v_lshl_add_u64 v[96:97], v[102:103], 0, v[96:97]
	v_lshl_add_u64 v[96:97], v[162:163], 2, v[96:97]
	global_load_dword v73, v[96:97], off
	v_add_u32_e32 v96, v144, v120
	v_ashrrev_i32_e32 v97, 31, v96
	v_lshl_add_u64 v[96:97], v[96:97], 2, s[78:79]
	global_load_dword v77, v[96:97], off
	s_waitcnt vmcnt(0)
	v_fmac_f32_e32 v73, v58, v77
	global_store_dword v[90:91], v73, off
	v_or_b32_e32 v90, v122, v134
	v_cmp_lt_i32_e64 s[30:31], s64, v90
	s_cbranch_vccnz .LBB0_1099
	s_and_saveexec_b64 s[2:3], s[30:31]
	s_xor_b64 s[2:3], exec, s[2:3]
	v_mov_b32_e32 v91, v163
	v_add_u32_e32 v102, 0xffffc000, v90
	v_mov_b32_e32 v103, v163
	v_mov_b64_e32 v[96:97], v[90:91]
	s_or_saveexec_b64 s[2:3], s[2:3]
	v_readlane_b32 s30, v254, 2
	v_readlane_b32 s31, v254, 3
	s_nop 1
	v_mov_b64_e32 v[106:107], s[30:31]
	s_xor_b64 exec, exec, s[2:3]
	v_ashrrev_i32_e32 v91, 31, v90
	v_mov_b64_e32 v[106:107], s[0:1]
	v_mov_b64_e32 v[102:103], v[90:91]
	v_mov_b64_e32 v[96:97], v[90:91]
	s_or_b64 exec, exec, s[2:3]
	s_mov_b64 s[2:3], 0

; DI const float* xrow_ptr(const Params& p, int l, int row) {
;   if (l > 0) return p.out + (size_t)row * D;
;   return row < NP ? p.in[0] + (size_t)row * D : p.in[1] + (size_t)(row - NP) * D;
; }
; DI void phase7(const Params& p, int l, unsigned char* smem) {
;     ...
;     foreach_acc(acc, m0, n0, [&](int row, int col, float v) {
;       float xo = xrow_ptr(p, l, row)[col];
;       float gt = mod[(l * 10 + bidx_of(row)) * 3072 + 2048 + col];
;       p.out[(size_t)row * D + col] = xo + gt * v;
;     });
.LBB0_1101:
	v_subrev_u32_e32 v106, s0, v106
	v_and_or_b32 v106, v106, 40, v242
	ds_read_b64 v[106:107], v106
	v_lshlrev_b64 v[102:103], 12, v[102:103]
	v_cmp_gt_i32_e32 vcc, s50, v90
	v_or_b32_e32 v135, 24, v123
	v_cmp_lt_i32_e64 s[30:31], s64, v90
	s_mov_b64 s[2:3], -1
	s_waitcnt lgkmcnt(0)
	v_lshl_add_u64 v[102:103], v[106:107], 0, v[102:103]
	v_add_u32_e32 v106, 0xffffc000, v90
	v_lshrrev_b32_e32 v58, 4, v106
	v_or_b32_e32 v58, 2, v58
	v_cndmask_b32_e32 v58, v58, v121, vcc
	v_add_u32_e32 v58, s94, v58
	v_lshl_add_u64 v[102:103], v[162:163], 2, v[102:103]
	v_mul_lo_u32 v145, v58, s74
	global_load_dword v73, v[102:103], off
	v_add_u32_e32 v102, v145, v120
	v_ashrrev_i32_e32 v103, 31, v102
	v_lshl_add_u64 v[102:103], v[102:103], 2, s[78:79]
	global_load_dword v58, v[102:103], off
	s_and_b64 vcc, exec, s[6:7]
	s_waitcnt vmcnt(0)
	v_fmac_f32_e32 v73, v59, v58
	v_lshlrev_b64 v[58:59], 12, v[96:97]
	v_lshl_add_u64 v[58:59], v[64:65], 0, v[58:59]
	global_store_dword v[58:59], v73, off
	v_or_b32_e32 v58, v122, v135
	v_cmp_lt_i32_e64 s[34:35], s64, v58
	s_cbranch_vccnz .LBB0_1107
	s_and_saveexec_b64 s[2:3], s[34:35]
	s_xor_b64 s[2:3], exec, s[2:3]
	v_mov_b32_e32 v59, v163
	v_add_u32_e32 v102, 0xffffc000, v58
	v_mov_b32_e32 v103, v163
	v_mov_b64_e32 v[96:97], v[58:59]
	s_or_saveexec_b64 s[2:3], s[2:3]
	v_readlane_b32 s34, v254, 2
	v_readlane_b32 s35, v254, 3
	s_nop 1
	v_mov_b64_e32 v[108:109], s[34:35]
	s_xor_b64 exec, exec, s[2:3]
	v_ashrrev_i32_e32 v59, 31, v58
	v_mov_b64_e32 v[108:109], s[0:1]
	v_mov_b64_e32 v[102:103], v[58:59]
	v_mov_b64_e32 v[96:97], v[58:59]
	s_or_b64 exec, exec, s[2:3]
	s_mov_b64 s[2:3], 0

; DI const float* xrow_ptr(const Params& p, int l, int row) {
;   if (l > 0) return p.out + (size_t)row * D;
;   return row < NP ? p.in[0] + (size_t)row * D : p.in[1] + (size_t)(row - NP) * D;
; }
; DI void phase7(const Params& p, int l, unsigned char* smem) {
;     ...
;     foreach_acc(acc, m0, n0, [&](int row, int col, float v) {
;       float xo = xrow_ptr(p, l, row)[col];
;       float gt = mod[(l * 10 + bidx_of(row)) * 3072 + 2048 + col];
;       p.out[(size_t)row * D + col] = xo + gt * v;
;     });
.LBB0_1109:
	v_subrev_u32_e32 v108, s0, v108
	v_and_or_b32 v108, v108, 40, v242
	ds_read_b64 v[108:109], v108
	v_lshlrev_b64 v[102:103], 12, v[102:103]
	v_cmp_gt_i32_e32 vcc, s50, v58
	v_lshlrev_b64 v[96:97], 12, v[96:97]
	v_lshl_add_u64 v[96:97], v[64:65], 0, v[96:97]
	v_or_b32_e32 v136, 25, v123
	v_cmp_lt_i32_e64 s[34:35], s64, v58
	s_mov_b64 s[2:3], -1
	s_waitcnt lgkmcnt(0)
	v_lshl_add_u64 v[102:103], v[108:109], 0, v[102:103]
	v_add_u32_e32 v108, 0xffffc000, v58
	v_lshrrev_b32_e32 v77, 4, v108
	v_or_b32_e32 v77, 2, v77
	v_cndmask_b32_e32 v77, v77, v121, vcc
	v_add_u32_e32 v77, s94, v77
	v_lshl_add_u64 v[102:103], v[162:163], 2, v[102:103]
	v_mul_lo_u32 v146, v77, s74
	global_load_dword v73, v[102:103], off
	v_add_u32_e32 v102, v146, v120
	v_ashrrev_i32_e32 v103, 31, v102
	v_lshl_add_u64 v[102:103], v[102:103], 2, s[78:79]
	global_load_dword v77, v[102:103], off
	s_and_b64 vcc, exec, s[6:7]
	s_waitcnt vmcnt(0)
	v_fmac_f32_e32 v73, v60, v77
	global_store_dword v[96:97], v73, off
	v_or_b32_e32 v96, v122, v136
	v_cmp_lt_i32_e64 s[36:37], s64, v96
	s_cbranch_vccnz .LBB0_1115
	s_and_saveexec_b64 s[2:3], s[36:37]
	s_xor_b64 s[2:3], exec, s[2:3]
	v_mov_b32_e32 v97, v163
	v_add_u32_e32 v110, 0xffffc000, v96
	v_mov_b32_e32 v111, v163
	v_mov_b64_e32 v[102:103], v[96:97]
	s_or_saveexec_b64 s[2:3], s[2:3]
	v_readlane_b32 s36, v254, 2
	v_readlane_b32 s37, v254, 3
	s_nop 1
	v_mov_b64_e32 v[112:113], s[36:37]
	s_xor_b64 exec, exec, s[2:3]
	v_ashrrev_i32_e32 v97, 31, v96
	v_mov_b64_e32 v[112:113], s[0:1]
	v_mov_b64_e32 v[110:111], v[96:97]
	v_mov_b64_e32 v[102:103], v[96:97]
	s_or_b64 exec, exec, s[2:3]
	s_mov_b64 s[2:3], 0

; DI const float* xrow_ptr(const Params& p, int l, int row) {
;   if (l > 0) return p.out + (size_t)row * D;
;   return row < NP ? p.in[0] + (size_t)row * D : p.in[1] + (size_t)(row - NP) * D;
; }
; DI void phase7(const Params& p, int l, unsigned char* smem) {
;     ...
;     foreach_acc(acc, m0, n0, [&](int row, int col, float v) {
;       float xo = xrow_ptr(p, l, row)[col];
;       float gt = mod[(l * 10 + bidx_of(row)) * 3072 + 2048 + col];
;       p.out[(size_t)row * D + col] = xo + gt * v;
;     });
.LBB0_1117:
	v_subrev_u32_e32 v112, s0, v112
	v_and_or_b32 v112, v112, 40, v242
	ds_read_b64 v[112:113], v112
	v_lshlrev_b64 v[110:111], 12, v[110:111]
	v_cmp_gt_i32_e32 vcc, s50, v96
	v_or_b32_e32 v137, 26, v123
	v_cmp_lt_i32_e64 s[36:37], s64, v96
	s_mov_b64 s[2:3], -1
	s_waitcnt lgkmcnt(0)
	v_lshl_add_u64 v[110:111], v[112:113], 0, v[110:111]
	v_lshl_add_u64 v[110:111], v[162:163], 2, v[110:111]
	global_load_dword v73, v[110:111], off
	v_add_u32_e32 v110, 0xffffc000, v96
	v_lshrrev_b32_e32 v60, 4, v110
	v_or_b32_e32 v60, 2, v60
	v_cndmask_b32_e32 v60, v60, v121, vcc
	v_add_u32_e32 v60, s94, v60
	v_mul_lo_u32 v147, v60, s74
	v_add_u32_e32 v112, v147, v120
	v_ashrrev_i32_e32 v113, 31, v112
	v_lshl_add_u64 v[112:113], v[112:113], 2, s[78:79]
	global_load_dword v60, v[112:113], off
	s_and_b64 vcc, exec, s[6:7]
	s_waitcnt vmcnt(0)
	v_fmac_f32_e32 v73, v61, v60
	v_lshlrev_b64 v[60:61], 12, v[102:103]
	v_lshl_add_u64 v[60:61], v[64:65], 0, v[60:61]
	global_store_dword v[60:61], v73, off
	v_or_b32_e32 v60, v122, v137
	v_cmp_lt_i32_e64 s[38:39], s64, v60
	s_cbranch_vccnz .LBB0_1123
	s_and_saveexec_b64 s[2:3], s[38:39]
	s_xor_b64 s[2:3], exec, s[2:3]
	v_mov_b32_e32 v61, v163
	v_add_u32_e32 v112, 0xffffc000, v60
	v_mov_b32_e32 v113, v163
	v_mov_b64_e32 v[102:103], v[60:61]
	s_or_saveexec_b64 s[2:3], s[2:3]
	v_readlane_b32 s38, v254, 2
	v_readlane_b32 s39, v254, 3
	s_nop 1
	v_mov_b64_e32 v[114:115], s[38:39]
	s_xor_b64 exec, exec, s[2:3]
	v_ashrrev_i32_e32 v61, 31, v60
	v_mov_b64_e32 v[114:115], s[0:1]
	v_mov_b64_e32 v[112:113], v[60:61]
	v_mov_b64_e32 v[102:103], v[60:61]
	s_or_b64 exec, exec, s[2:3]
	s_mov_b64 s[2:3], 0

; DI const float* xrow_ptr(const Params& p, int l, int row) {
;   if (l > 0) return p.out + (size_t)row * D;
;   return row < NP ? p.in[0] + (size_t)row * D : p.in[1] + (size_t)(row - NP) * D;
; }
; DI void phase7(const Params& p, int l, unsigned char* smem) {
;     ...
;     foreach_acc(acc, m0, n0, [&](int row, int col, float v) {
;       float xo = xrow_ptr(p, l, row)[col];
;       float gt = mod[(l * 10 + bidx_of(row)) * 3072 + 2048 + col];
;       p.out[(size_t)row * D + col] = xo + gt * v;
;     });
.LBB0_1125:
	v_subrev_u32_e32 v114, s0, v114
	v_and_or_b32 v114, v114, 40, v242
	ds_read_b64 v[114:115], v114
	v_lshlrev_b64 v[112:113], 12, v[112:113]
	v_cmp_gt_i32_e32 vcc, s50, v60
	v_lshlrev_b64 v[102:103], 12, v[102:103]
	v_lshl_add_u64 v[102:103], v[64:65], 0, v[102:103]
	v_or_b32_e32 v138, 27, v123
	v_cmp_lt_i32_e64 s[38:39], s64, v60
	s_mov_b64 s[2:3], -1
	s_waitcnt lgkmcnt(0)
	v_lshl_add_u64 v[112:113], v[114:115], 0, v[112:113]
	v_lshl_add_u64 v[112:113], v[162:163], 2, v[112:113]
	global_load_dword v73, v[112:113], off
	v_add_u32_e32 v112, 0xffffc000, v60
	v_lshrrev_b32_e32 v77, 4, v112
	v_or_b32_e32 v77, 2, v77
	v_cndmask_b32_e32 v77, v77, v121, vcc
	v_add_u32_e32 v77, s94, v77
	v_mul_lo_u32 v148, v77, s74
	v_add_u32_e32 v114, v148, v120
	v_ashrrev_i32_e32 v115, 31, v114
	v_lshl_add_u64 v[114:115], v[114:115], 2, s[78:79]
	global_load_dword v77, v[114:115], off
	s_and_b64 vcc, exec, s[6:7]
	s_waitcnt vmcnt(0)
	v_fmac_f32_e32 v73, v62, v77
	global_store_dword v[102:103], v73, off
	v_or_b32_e32 v102, v122, v138
	v_cmp_lt_i32_e64 s[40:41], s64, v102
	s_cbranch_vccnz .LBB0_1131
	s_and_saveexec_b64 s[2:3], s[40:41]
	s_xor_b64 s[2:3], exec, s[2:3]
	v_mov_b32_e32 v103, v163
	v_add_u32_e32 v116, 0xffffc000, v102
	v_mov_b32_e32 v117, v163
	v_mov_b64_e32 v[114:115], v[102:103]
	s_or_saveexec_b64 s[2:3], s[2:3]
	v_readlane_b32 s40, v254, 2
	v_readlane_b32 s41, v254, 3
	s_nop 1
	v_mov_b64_e32 v[118:119], s[40:41]
	s_xor_b64 exec, exec, s[2:3]
	v_ashrrev_i32_e32 v103, 31, v102
	v_mov_b64_e32 v[118:119], s[0:1]
	v_mov_b64_e32 v[116:117], v[102:103]
	v_mov_b64_e32 v[114:115], v[102:103]
	s_or_b64 exec, exec, s[2:3]
	s_mov_b64 s[2:3], 0

; DI const float* xrow_ptr(const Params& p, int l, int row) {
;   if (l > 0) return p.out + (size_t)row * D;
;   return row < NP ? p.in[0] + (size_t)row * D : p.in[1] + (size_t)(row - NP) * D;
; }
; DI void phase7(const Params& p, int l, unsigned char* smem) {
;     ...
;     foreach_acc(acc, m0, n0, [&](int row, int col, float v) {
;       float xo = xrow_ptr(p, l, row)[col];
;       float gt = mod[(l * 10 + bidx_of(row)) * 3072 + 2048 + col];
;       p.out[(size_t)row * D + col] = xo + gt * v;
;     });
.LBB0_1133:
	v_subrev_u32_e32 v118, s0, v118
	v_and_or_b32 v118, v118, 40, v242
	ds_read_b64 v[118:119], v118
	v_add_u32_e32 v62, 0xffffc000, v102
	v_lshrrev_b32_e32 v77, 4, v62
	v_cmp_gt_i32_e32 vcc, s50, v102
	v_or_b32_e32 v77, 2, v77
	v_lshlrev_b64 v[116:117], 12, v[116:117]
	v_cndmask_b32_e32 v77, v77, v121, vcc
	v_add_u32_e32 v77, s94, v77
	v_lshlrev_b64 v[114:115], 12, v[114:115]
	v_cmp_lt_i32_e64 s[40:41], s64, v102
	v_lshl_add_u64 v[114:115], v[64:65], 0, v[114:115]
	s_mov_b64 s[2:3], -1
	s_and_b64 vcc, exec, s[6:7]
	s_waitcnt lgkmcnt(0)
	v_lshl_add_u64 v[116:117], v[118:119], 0, v[116:117]
	v_lshl_add_u64 v[116:117], v[162:163], 2, v[116:117]
	v_mul_lo_u32 v119, v77, s74
	global_load_dword v73, v[116:117], off
	v_add_u32_e32 v116, v119, v120
	v_ashrrev_i32_e32 v117, 31, v116
	v_lshl_add_u64 v[116:117], v[116:117], 2, s[78:79]
	global_load_dword v77, v[116:117], off
	s_waitcnt vmcnt(0)
	v_fmac_f32_e32 v73, v63, v77
	global_store_dword v[114:115], v73, off
	s_cbranch_vccnz .LBB0_1139
	s_and_saveexec_b64 s[2:3], s[8:9]
	s_xor_b64 s[2:3], exec, s[2:3]
	v_mov_b32_e32 v73, v163
	v_mov_b32_e32 v114, v66
	v_mov_b32_e32 v115, v163
	s_or_saveexec_b64 s[2:3], s[2:3]
	v_readlane_b32 s8, v254, 2
	v_readlane_b32 s9, v254, 3
	s_nop 1
	v_mov_b64_e32 v[116:117], s[8:9]
	s_xor_b64 exec, exec, s[2:3]
	v_mov_b64_e32 v[116:117], s[0:1]
	v_mov_b64_e32 v[72:73], v[66:67]
	v_mov_b64_e32 v[114:115], v[66:67]
	s_or_b64 exec, exec, s[2:3]
	s_mov_b64 s[2:3], 0

; DI const float* xrow_ptr(const Params& p, int l, int row) {
;   if (l > 0) return p.out + (size_t)row * D;
;   return row < NP ? p.in[0] + (size_t)row * D : p.in[1] + (size_t)(row - NP) * D;
; }
; DI void phase7(const Params& p, int l, unsigned char* smem) {
;     ...
;     foreach_acc(acc, m0, n0, [&](int row, int col, float v) {
;       float xo = xrow_ptr(p, l, row)[col];
;       float gt = mod[(l * 10 + bidx_of(row)) * 3072 + 2048 + col];
;       p.out[(size_t)row * D + col] = xo + gt * v;
;     });
.LBB0_1141:
	v_subrev_u32_e32 v66, s0, v116
	v_and_or_b32 v66, v66, 40, v242
	ds_read_b64 v[66:67], v66
	v_lshlrev_b64 v[72:73], 12, v[72:73]
	v_add_u32_e32 v118, 0x820, v162
	s_mov_b64 s[2:3], -1
	s_and_b64 vcc, exec, s[6:7]
	s_waitcnt lgkmcnt(0)
	v_lshl_add_u64 v[66:67], v[66:67], 0, v[72:73]
	v_lshl_add_u64 v[66:67], v[162:163], 2, v[66:67]
	global_load_dword v63, v[66:67], off offset:128
	v_add_u32_e32 v66, v81, v118
	v_ashrrev_i32_e32 v67, 31, v66
	v_lshl_add_u64 v[66:67], v[66:67], 2, s[78:79]
	global_load_dword v66, v[66:67], off
	s_waitcnt vmcnt(0)
	v_fmac_f32_e32 v63, v32, v66
	v_lshlrev_b64 v[66:67], 12, v[114:115]
	v_lshl_add_u64 v[66:67], v[64:65], 0, v[66:67]
	global_store_dword v[66:67], v63, off offset:128
	s_cbranch_vccnz .LBB0_1147
	s_and_saveexec_b64 s[2:3], s[10:11]
	s_xor_b64 s[2:3], exec, s[2:3]
	v_mov_b32_e32 v77, v163
	v_mov_b32_e32 v66, v68
	v_mov_b32_e32 v67, v163
	s_or_saveexec_b64 s[2:3], s[2:3]
	v_readlane_b32 s8, v254, 2
	v_readlane_b32 s9, v254, 3
	s_nop 1
	v_mov_b64_e32 v[72:73], s[8:9]
	s_xor_b64 exec, exec, s[2:3]
	v_mov_b64_e32 v[72:73], s[0:1]
	v_mov_b64_e32 v[76:77], v[68:69]
	v_mov_b64_e32 v[66:67], v[68:69]
	s_or_b64 exec, exec, s[2:3]
	s_mov_b64 s[2:3], 0

; DI const float* xrow_ptr(const Params& p, int l, int row) {
;   if (l > 0) return p.out + (size_t)row * D;
;   return row < NP ? p.in[0] + (size_t)row * D : p.in[1] + (size_t)(row - NP) * D;
; }
; DI void phase7(const Params& p, int l, unsigned char* smem) {
;     ...
;     foreach_acc(acc, m0, n0, [&](int row, int col, float v) {
;       float xo = xrow_ptr(p, l, row)[col];
;       float gt = mod[(l * 10 + bidx_of(row)) * 3072 + 2048 + col];
;       p.out[(size_t)row * D + col] = xo + gt * v;
;     });
.LBB0_1149:
	v_subrev_u32_e32 v68, s0, v72
	v_and_or_b32 v68, v68, 40, v242
	ds_read_b64 v[68:69], v68
	v_lshlrev_b64 v[72:73], 12, v[76:77]
	s_mov_b64 s[2:3], -1
	s_and_b64 vcc, exec, s[6:7]
	s_waitcnt lgkmcnt(0)
	v_lshl_add_u64 v[68:69], v[68:69], 0, v[72:73]
	v_lshl_add_u64 v[68:69], v[162:163], 2, v[68:69]
	global_load_dword v63, v[68:69], off offset:128
	v_add_u32_e32 v68, v87, v118
	v_ashrrev_i32_e32 v69, 31, v68
	v_lshl_add_u64 v[68:69], v[68:69], 2, s[78:79]
	global_load_dword v32, v[68:69], off
	s_waitcnt vmcnt(0)
	v_fmac_f32_e32 v63, v33, v32
	v_lshlrev_b64 v[32:33], 12, v[66:67]
	v_lshl_add_u64 v[32:33], v[64:65], 0, v[32:33]
	global_store_dword v[32:33], v63, off offset:128
	s_cbranch_vccnz .LBB0_1155
	s_and_saveexec_b64 s[2:3], s[12:13]
	s_xor_b64 s[2:3], exec, s[2:3]
	v_mov_b32_e32 v81, v163
	v_mov_b32_e32 v32, v48
	v_mov_b32_e32 v33, v163
	s_or_saveexec_b64 s[2:3], s[2:3]
	v_readlane_b32 s8, v254, 2
	v_readlane_b32 s9, v254, 3
	s_nop 1
	v_mov_b64_e32 v[66:67], s[8:9]
	s_xor_b64 exec, exec, s[2:3]
	v_mov_b64_e32 v[66:67], s[0:1]
	v_mov_b64_e32 v[80:81], v[48:49]
	v_mov_b64_e32 v[32:33], v[48:49]
	s_or_b64 exec, exec, s[2:3]
	s_mov_b64 s[2:3], 0

; DI const float* xrow_ptr(const Params& p, int l, int row) {
;   if (l > 0) return p.out + (size_t)row * D;
;   return row < NP ? p.in[0] + (size_t)row * D : p.in[1] + (size_t)(row - NP) * D;
; }
; DI void phase7(const Params& p, int l, unsigned char* smem) {
;     ...
;     foreach_acc(acc, m0, n0, [&](int row, int col, float v) {
;       float xo = xrow_ptr(p, l, row)[col];
;       float gt = mod[(l * 10 + bidx_of(row)) * 3072 + 2048 + col];
;       p.out[(size_t)row * D + col] = xo + gt * v;
;     });
.LBB0_1157:
	v_subrev_u32_e32 v48, s0, v66
	v_and_or_b32 v48, v48, 40, v242
	ds_read_b64 v[48:49], v48
	v_lshlrev_b64 v[66:67], 12, v[80:81]
	v_lshlrev_b64 v[32:33], 12, v[32:33]
	v_lshl_add_u64 v[32:33], v[64:65], 0, v[32:33]
	s_mov_b64 s[2:3], -1
	s_and_b64 vcc, exec, s[6:7]
	s_waitcnt lgkmcnt(0)
	v_lshl_add_u64 v[48:49], v[48:49], 0, v[66:67]
	v_lshl_add_u64 v[48:49], v[162:163], 2, v[48:49]
	global_load_dword v63, v[48:49], off offset:128
	v_add_u32_e32 v48, v93, v118
	v_ashrrev_i32_e32 v49, 31, v48
	v_lshl_add_u64 v[48:49], v[48:49], 2, s[78:79]
	global_load_dword v48, v[48:49], off
	s_waitcnt vmcnt(0)
	v_fmac_f32_e32 v63, v34, v48
	global_store_dword v[32:33], v63, off offset:128
	s_cbranch_vccnz .LBB0_1163
	s_and_saveexec_b64 s[2:3], s[14:15]
	s_xor_b64 s[2:3], exec, s[2:3]
	v_mov_b32_e32 v83, v163
	v_mov_b32_e32 v32, v70
	v_mov_b32_e32 v33, v163
	s_or_saveexec_b64 s[2:3], s[2:3]
	v_readlane_b32 s8, v254, 2
	v_readlane_b32 s9, v254, 3
	s_nop 1
	v_mov_b64_e32 v[48:49], s[8:9]
	s_xor_b64 exec, exec, s[2:3]
	v_mov_b64_e32 v[48:49], s[0:1]
	v_mov_b64_e32 v[82:83], v[70:71]
	v_mov_b64_e32 v[32:33], v[70:71]
	s_or_b64 exec, exec, s[2:3]
	s_mov_b64 s[2:3], 0

; DI const float* xrow_ptr(const Params& p, int l, int row) {
;   if (l > 0) return p.out + (size_t)row * D;
;   return row < NP ? p.in[0] + (size_t)row * D : p.in[1] + (size_t)(row - NP) * D;
; }
; DI void phase7(const Params& p, int l, unsigned char* smem) {
;     ...
;     foreach_acc(acc, m0, n0, [&](int row, int col, float v) {
;       float xo = xrow_ptr(p, l, row)[col];
;       float gt = mod[(l * 10 + bidx_of(row)) * 3072 + 2048 + col];
;       p.out[(size_t)row * D + col] = xo + gt * v;
;     });
.LBB0_1165:
	v_subrev_u32_e32 v48, s0, v48
	v_and_or_b32 v48, v48, 40, v242
	ds_read_b64 v[48:49], v48
	v_lshlrev_b64 v[66:67], 12, v[82:83]
	v_lshlrev_b64 v[32:33], 12, v[32:33]
	v_lshl_add_u64 v[32:33], v[64:65], 0, v[32:33]
	s_mov_b64 s[2:3], -1
	s_and_b64 vcc, exec, s[6:7]
	s_waitcnt lgkmcnt(0)
	v_lshl_add_u64 v[48:49], v[48:49], 0, v[66:67]
	v_lshl_add_u64 v[48:49], v[162:163], 2, v[48:49]
	global_load_dword v34, v[48:49], off offset:128
	v_add_u32_e32 v48, v99, v118
	v_ashrrev_i32_e32 v49, 31, v48
	v_lshl_add_u64 v[48:49], v[48:49], 2, s[78:79]
	global_load_dword v48, v[48:49], off
	s_waitcnt vmcnt(0)
	v_fmac_f32_e32 v34, v35, v48
	global_store_dword v[32:33], v34, off offset:128
	s_cbranch_vccnz .LBB0_1171
	s_and_saveexec_b64 s[2:3], s[16:17]
	s_xor_b64 s[2:3], exec, s[2:3]
	v_mov_b32_e32 v87, v163
	v_mov_b32_e32 v32, v50
	v_mov_b32_e32 v33, v163
	s_or_saveexec_b64 s[2:3], s[2:3]
	v_readlane_b32 s8, v254, 2
	v_readlane_b32 s9, v254, 3
	s_nop 1
	v_mov_b64_e32 v[34:35], s[8:9]
	s_xor_b64 exec, exec, s[2:3]
	v_mov_b64_e32 v[34:35], s[0:1]
	v_mov_b64_e32 v[86:87], v[50:51]
	v_mov_b64_e32 v[32:33], v[50:51]
	s_or_b64 exec, exec, s[2:3]
	s_mov_b64 s[2:3], 0

; DI const float* xrow_ptr(const Params& p, int l, int row) {
;   if (l > 0) return p.out + (size_t)row * D;
;   return row < NP ? p.in[0] + (size_t)row * D : p.in[1] + (size_t)(row - NP) * D;
; }
; DI void phase7(const Params& p, int l, unsigned char* smem) {
;     ...
;     foreach_acc(acc, m0, n0, [&](int row, int col, float v) {
;       float xo = xrow_ptr(p, l, row)[col];
;       float gt = mod[(l * 10 + bidx_of(row)) * 3072 + 2048 + col];
;       p.out[(size_t)row * D + col] = xo + gt * v;
;     });
.LBB0_1173:
	v_subrev_u32_e32 v34, s0, v34
	v_and_or_b32 v34, v34, 40, v242
	ds_read_b64 v[34:35], v34
	v_lshlrev_b64 v[48:49], 12, v[86:87]
	v_lshlrev_b64 v[32:33], 12, v[32:33]
	v_lshl_add_u64 v[32:33], v[64:65], 0, v[32:33]
	s_mov_b64 s[2:3], -1
	s_and_b64 vcc, exec, s[6:7]
	s_waitcnt lgkmcnt(0)
	v_lshl_add_u64 v[34:35], v[34:35], 0, v[48:49]
	v_lshl_add_u64 v[34:35], v[162:163], 2, v[34:35]
	global_load_dword v48, v[34:35], off offset:128
	v_add_u32_e32 v34, v105, v118
	v_ashrrev_i32_e32 v35, 31, v34
	v_lshl_add_u64 v[34:35], v[34:35], 2, s[78:79]
	global_load_dword v34, v[34:35], off
	s_waitcnt vmcnt(0)
	v_fmac_f32_e32 v48, v36, v34
	global_store_dword v[32:33], v48, off offset:128
	s_cbranch_vccnz .LBB0_1179
	s_and_saveexec_b64 s[2:3], s[18:19]
	s_xor_b64 s[2:3], exec, s[2:3]
	v_mov_b32_e32 v89, v163
	v_mov_b32_e32 v32, v74
	v_mov_b32_e32 v33, v163
	s_or_saveexec_b64 s[2:3], s[2:3]
	v_readlane_b32 s8, v254, 2
	v_readlane_b32 s9, v254, 3
	s_nop 1
	v_mov_b64_e32 v[34:35], s[8:9]
	s_xor_b64 exec, exec, s[2:3]
	v_mov_b64_e32 v[34:35], s[0:1]
	v_mov_b64_e32 v[88:89], v[74:75]
	v_mov_b64_e32 v[32:33], v[74:75]
	s_or_b64 exec, exec, s[2:3]
	s_mov_b64 s[2:3], 0

; DI const float* xrow_ptr(const Params& p, int l, int row) {
;   if (l > 0) return p.out + (size_t)row * D;
;   return row < NP ? p.in[0] + (size_t)row * D : p.in[1] + (size_t)(row - NP) * D;
; }
; DI void phase7(const Params& p, int l, unsigned char* smem) {
;     ...
;     foreach_acc(acc, m0, n0, [&](int row, int col, float v) {
;       float xo = xrow_ptr(p, l, row)[col];
;       float gt = mod[(l * 10 + bidx_of(row)) * 3072 + 2048 + col];
;       p.out[(size_t)row * D + col] = xo + gt * v;
;     });
.LBB0_1181:
	v_subrev_u32_e32 v34, s0, v34
	v_and_or_b32 v34, v34, 40, v242
	ds_read_b64 v[34:35], v34
	v_lshlrev_b64 v[48:49], 12, v[88:89]
	v_lshlrev_b64 v[32:33], 12, v[32:33]
	v_lshl_add_u64 v[32:33], v[64:65], 0, v[32:33]
	s_mov_b64 s[2:3], -1
	s_and_b64 vcc, exec, s[6:7]
	s_waitcnt lgkmcnt(0)
	v_lshl_add_u64 v[34:35], v[34:35], 0, v[48:49]
	v_lshl_add_u64 v[34:35], v[162:163], 2, v[34:35]
	global_load_dword v36, v[34:35], off offset:128
	v_add_u32_e32 v34, v139, v118
	v_ashrrev_i32_e32 v35, 31, v34
	v_lshl_add_u64 v[34:35], v[34:35], 2, s[78:79]
	global_load_dword v34, v[34:35], off
	s_waitcnt vmcnt(0)
	v_fmac_f32_e32 v36, v37, v34
	global_store_dword v[32:33], v36, off offset:128
	s_cbranch_vccnz .LBB0_1187
	s_and_saveexec_b64 s[2:3], s[20:21]
	s_xor_b64 s[2:3], exec, s[2:3]
	v_mov_b32_e32 v93, v163
	v_mov_b32_e32 v32, v52
	v_mov_b32_e32 v33, v163
	s_or_saveexec_b64 s[2:3], s[2:3]
	v_readlane_b32 s8, v254, 2
	v_readlane_b32 s9, v254, 3
	s_nop 1
	v_mov_b64_e32 v[34:35], s[8:9]
	s_xor_b64 exec, exec, s[2:3]
	v_mov_b64_e32 v[34:35], s[0:1]
	v_mov_b64_e32 v[92:93], v[52:53]
	v_mov_b64_e32 v[32:33], v[52:53]
	s_or_b64 exec, exec, s[2:3]
	s_mov_b64 s[2:3], 0

; DI const float* xrow_ptr(const Params& p, int l, int row) {
;   if (l > 0) return p.out + (size_t)row * D;
;   return row < NP ? p.in[0] + (size_t)row * D : p.in[1] + (size_t)(row - NP) * D;
; }
; DI void phase7(const Params& p, int l, unsigned char* smem) {
;     ...
;     foreach_acc(acc, m0, n0, [&](int row, int col, float v) {
;       float xo = xrow_ptr(p, l, row)[col];
;       float gt = mod[(l * 10 + bidx_of(row)) * 3072 + 2048 + col];
;       p.out[(size_t)row * D + col] = xo + gt * v;
;     });
.LBB0_1189:
	v_subrev_u32_e32 v34, s0, v34
	v_and_or_b32 v34, v34, 40, v242
	ds_read_b64 v[34:35], v34
	v_lshlrev_b64 v[36:37], 12, v[92:93]
	v_lshlrev_b64 v[32:33], 12, v[32:33]
	v_lshl_add_u64 v[32:33], v[64:65], 0, v[32:33]
	s_mov_b64 s[2:3], -1
	s_and_b64 vcc, exec, s[6:7]
	s_waitcnt lgkmcnt(0)
	v_lshl_add_u64 v[34:35], v[34:35], 0, v[36:37]
	v_lshl_add_u64 v[34:35], v[162:163], 2, v[34:35]
	global_load_dword v36, v[34:35], off offset:128
	v_add_u32_e32 v34, v140, v118
	v_ashrrev_i32_e32 v35, 31, v34
	v_lshl_add_u64 v[34:35], v[34:35], 2, s[78:79]
	global_load_dword v34, v[34:35], off
	s_waitcnt vmcnt(0)
	v_fmac_f32_e32 v36, v38, v34
	global_store_dword v[32:33], v36, off offset:128
	s_cbranch_vccnz .LBB0_1195
	s_and_saveexec_b64 s[2:3], s[22:23]
	s_xor_b64 s[2:3], exec, s[2:3]
	v_mov_b32_e32 v95, v163
	v_mov_b32_e32 v32, v78
	v_mov_b32_e32 v33, v163
	s_or_saveexec_b64 s[2:3], s[2:3]
	v_readlane_b32 s8, v254, 2
	v_readlane_b32 s9, v254, 3
	s_nop 1
	v_mov_b64_e32 v[34:35], s[8:9]
	s_xor_b64 exec, exec, s[2:3]
	v_mov_b64_e32 v[34:35], s[0:1]
	v_mov_b64_e32 v[94:95], v[78:79]
	v_mov_b64_e32 v[32:33], v[78:79]
	s_or_b64 exec, exec, s[2:3]
	s_mov_b64 s[2:3], 0

; DI const float* xrow_ptr(const Params& p, int l, int row) {
;   if (l > 0) return p.out + (size_t)row * D;
;   return row < NP ? p.in[0] + (size_t)row * D : p.in[1] + (size_t)(row - NP) * D;
; }
; DI void phase7(const Params& p, int l, unsigned char* smem) {
;     ...
;     foreach_acc(acc, m0, n0, [&](int row, int col, float v) {
;       float xo = xrow_ptr(p, l, row)[col];
;       float gt = mod[(l * 10 + bidx_of(row)) * 3072 + 2048 + col];
;       p.out[(size_t)row * D + col] = xo + gt * v;
;     });
.LBB0_1197:
	v_subrev_u32_e32 v34, s0, v34
	v_and_or_b32 v34, v34, 40, v242
	ds_read_b64 v[34:35], v34
	v_lshlrev_b64 v[36:37], 12, v[94:95]
	v_lshlrev_b64 v[32:33], 12, v[32:33]
	v_lshl_add_u64 v[32:33], v[64:65], 0, v[32:33]
	s_mov_b64 s[2:3], -1
	s_and_b64 vcc, exec, s[6:7]
	s_waitcnt lgkmcnt(0)
	v_lshl_add_u64 v[34:35], v[34:35], 0, v[36:37]
	v_lshl_add_u64 v[34:35], v[162:163], 2, v[34:35]
	global_load_dword v36, v[34:35], off offset:128
	v_add_u32_e32 v34, v141, v118
	v_ashrrev_i32_e32 v35, 31, v34
	v_lshl_add_u64 v[34:35], v[34:35], 2, s[78:79]
	global_load_dword v34, v[34:35], off
	s_waitcnt vmcnt(0)
	v_fmac_f32_e32 v36, v39, v34
	global_store_dword v[32:33], v36, off offset:128
	s_cbranch_vccnz .LBB0_1203
	s_and_saveexec_b64 s[2:3], s[24:25]
	s_xor_b64 s[2:3], exec, s[2:3]
	v_mov_b32_e32 v99, v163
	v_mov_b32_e32 v32, v54
	v_mov_b32_e32 v33, v163
	s_or_saveexec_b64 s[2:3], s[2:3]
	v_readlane_b32 s8, v254, 2
	v_readlane_b32 s9, v254, 3
	s_nop 1
	v_mov_b64_e32 v[34:35], s[8:9]
	s_xor_b64 exec, exec, s[2:3]
	v_mov_b64_e32 v[34:35], s[0:1]
	v_mov_b64_e32 v[98:99], v[54:55]
	v_mov_b64_e32 v[32:33], v[54:55]
	s_or_b64 exec, exec, s[2:3]
	s_mov_b64 s[2:3], 0

; DI const float* xrow_ptr(const Params& p, int l, int row) {
;   if (l > 0) return p.out + (size_t)row * D;
;   return row < NP ? p.in[0] + (size_t)row * D : p.in[1] + (size_t)(row - NP) * D;
; }
; DI void phase7(const Params& p, int l, unsigned char* smem) {
;     ...
;     foreach_acc(acc, m0, n0, [&](int row, int col, float v) {
;       float xo = xrow_ptr(p, l, row)[col];
;       float gt = mod[(l * 10 + bidx_of(row)) * 3072 + 2048 + col];
;       p.out[(size_t)row * D + col] = xo + gt * v;
;     });
.LBB0_1205:
	v_subrev_u32_e32 v34, s0, v34
	v_and_or_b32 v34, v34, 40, v242
	ds_read_b64 v[34:35], v34
	v_lshlrev_b64 v[36:37], 12, v[98:99]
	v_lshlrev_b64 v[32:33], 12, v[32:33]
	v_lshl_add_u64 v[32:33], v[64:65], 0, v[32:33]
	s_mov_b64 s[2:3], -1
	s_and_b64 vcc, exec, s[6:7]
	s_waitcnt lgkmcnt(0)
	v_lshl_add_u64 v[34:35], v[34:35], 0, v[36:37]
	v_lshl_add_u64 v[34:35], v[162:163], 2, v[34:35]
	global_load_dword v36, v[34:35], off offset:128
	v_add_u32_e32 v34, v142, v118
	v_ashrrev_i32_e32 v35, 31, v34
	v_lshl_add_u64 v[34:35], v[34:35], 2, s[78:79]
	global_load_dword v34, v[34:35], off
	s_waitcnt vmcnt(0)
	v_fmac_f32_e32 v36, v40, v34
	global_store_dword v[32:33], v36, off offset:128
	s_cbranch_vccnz .LBB0_1211
	s_and_saveexec_b64 s[2:3], s[26:27]
	s_xor_b64 s[2:3], exec, s[2:3]
	v_mov_b32_e32 v101, v163
	v_mov_b32_e32 v32, v84
	v_mov_b32_e32 v33, v163
	s_or_saveexec_b64 s[2:3], s[2:3]
	v_readlane_b32 s8, v254, 2
	v_readlane_b32 s9, v254, 3
	s_nop 1
	v_mov_b64_e32 v[34:35], s[8:9]
	s_xor_b64 exec, exec, s[2:3]
	v_mov_b64_e32 v[34:35], s[0:1]
	v_mov_b64_e32 v[100:101], v[84:85]
	v_mov_b64_e32 v[32:33], v[84:85]
	s_or_b64 exec, exec, s[2:3]
	s_mov_b64 s[2:3], 0

; DI const float* xrow_ptr(const Params& p, int l, int row) {
;   if (l > 0) return p.out + (size_t)row * D;
;   return row < NP ? p.in[0] + (size_t)row * D : p.in[1] + (size_t)(row - NP) * D;
; }
; DI void phase7(const Params& p, int l, unsigned char* smem) {
;     ...
;     foreach_acc(acc, m0, n0, [&](int row, int col, float v) {
;       float xo = xrow_ptr(p, l, row)[col];
;       float gt = mod[(l * 10 + bidx_of(row)) * 3072 + 2048 + col];
;       p.out[(size_t)row * D + col] = xo + gt * v;
;     });
.LBB0_1213:
	v_subrev_u32_e32 v34, s0, v34
	v_and_or_b32 v34, v34, 40, v242
	ds_read_b64 v[34:35], v34
	v_lshlrev_b64 v[36:37], 12, v[100:101]
	v_lshlrev_b64 v[32:33], 12, v[32:33]
	v_lshl_add_u64 v[32:33], v[64:65], 0, v[32:33]
	s_mov_b64 s[2:3], -1
	s_and_b64 vcc, exec, s[6:7]
	s_waitcnt lgkmcnt(0)
	v_lshl_add_u64 v[34:35], v[34:35], 0, v[36:37]
	v_lshl_add_u64 v[34:35], v[162:163], 2, v[34:35]
	global_load_dword v36, v[34:35], off offset:128
	v_add_u32_e32 v34, v143, v118
	v_ashrrev_i32_e32 v35, 31, v34
	v_lshl_add_u64 v[34:35], v[34:35], 2, s[78:79]
	global_load_dword v34, v[34:35], off
	s_waitcnt vmcnt(0)
	v_fmac_f32_e32 v36, v41, v34
	global_store_dword v[32:33], v36, off offset:128
	s_cbranch_vccnz .LBB0_1219
	s_and_saveexec_b64 s[2:3], s[28:29]
	s_xor_b64 s[2:3], exec, s[2:3]
	v_mov_b32_e32 v105, v163
	v_mov_b32_e32 v32, v56
	v_mov_b32_e32 v33, v163
	s_or_saveexec_b64 s[2:3], s[2:3]
	v_readlane_b32 s8, v254, 2
	v_readlane_b32 s9, v254, 3
	s_nop 1
	v_mov_b64_e32 v[34:35], s[8:9]
	s_xor_b64 exec, exec, s[2:3]
	v_mov_b64_e32 v[34:35], s[0:1]
	v_mov_b64_e32 v[104:105], v[56:57]
	v_mov_b64_e32 v[32:33], v[56:57]
	s_or_b64 exec, exec, s[2:3]
	s_mov_b64 s[2:3], 0

; DI const float* xrow_ptr(const Params& p, int l, int row) {
;   if (l > 0) return p.out + (size_t)row * D;
;   return row < NP ? p.in[0] + (size_t)row * D : p.in[1] + (size_t)(row - NP) * D;
; }
; DI void phase7(const Params& p, int l, unsigned char* smem) {
;     ...
;     foreach_acc(acc, m0, n0, [&](int row, int col, float v) {
;       float xo = xrow_ptr(p, l, row)[col];
;       float gt = mod[(l * 10 + bidx_of(row)) * 3072 + 2048 + col];
;       p.out[(size_t)row * D + col] = xo + gt * v;
;     });
.LBB0_1221:
	v_subrev_u32_e32 v34, s0, v34
	v_and_or_b32 v34, v34, 40, v242
	ds_read_b64 v[34:35], v34
	v_lshlrev_b64 v[36:37], 12, v[104:105]
	v_lshlrev_b64 v[32:33], 12, v[32:33]
	v_lshl_add_u64 v[32:33], v[64:65], 0, v[32:33]
	s_mov_b64 s[2:3], -1
	s_and_b64 vcc, exec, s[6:7]
	s_waitcnt lgkmcnt(0)
	v_lshl_add_u64 v[34:35], v[34:35], 0, v[36:37]
	v_lshl_add_u64 v[34:35], v[162:163], 2, v[34:35]
	global_load_dword v36, v[34:35], off offset:128
	v_add_u32_e32 v34, v144, v118
	v_ashrrev_i32_e32 v35, 31, v34
	v_lshl_add_u64 v[34:35], v[34:35], 2, s[78:79]
	global_load_dword v34, v[34:35], off
	s_waitcnt vmcnt(0)
	v_fmac_f32_e32 v36, v42, v34
	global_store_dword v[32:33], v36, off offset:128
	s_cbranch_vccnz .LBB0_1227
	s_and_saveexec_b64 s[2:3], s[30:31]
	s_xor_b64 s[2:3], exec, s[2:3]
	v_mov_b32_e32 v107, v163
	v_mov_b32_e32 v32, v90
	v_mov_b32_e32 v33, v163
	s_or_saveexec_b64 s[2:3], s[2:3]
	v_readlane_b32 s8, v254, 2
	v_readlane_b32 s9, v254, 3
	s_nop 1
	v_mov_b64_e32 v[34:35], s[8:9]
	s_xor_b64 exec, exec, s[2:3]
	v_mov_b64_e32 v[34:35], s[0:1]
	v_mov_b64_e32 v[106:107], v[90:91]
	v_mov_b64_e32 v[32:33], v[90:91]
	s_or_b64 exec, exec, s[2:3]
	s_mov_b64 s[2:3], 0

; DI const float* xrow_ptr(const Params& p, int l, int row) {
;   if (l > 0) return p.out + (size_t)row * D;
;   return row < NP ? p.in[0] + (size_t)row * D : p.in[1] + (size_t)(row - NP) * D;
; }
; DI void phase7(const Params& p, int l, unsigned char* smem) {
;     ...
;     foreach_acc(acc, m0, n0, [&](int row, int col, float v) {
;       float xo = xrow_ptr(p, l, row)[col];
;       float gt = mod[(l * 10 + bidx_of(row)) * 3072 + 2048 + col];
;       p.out[(size_t)row * D + col] = xo + gt * v;
;     });
.LBB0_1229:
	v_subrev_u32_e32 v34, s0, v34
	v_and_or_b32 v34, v34, 40, v242
	ds_read_b64 v[34:35], v34
	v_lshlrev_b64 v[36:37], 12, v[106:107]
	v_lshlrev_b64 v[32:33], 12, v[32:33]
	v_lshl_add_u64 v[32:33], v[64:65], 0, v[32:33]
	s_mov_b64 s[2:3], -1
	s_and_b64 vcc, exec, s[6:7]
	s_waitcnt lgkmcnt(0)
	v_lshl_add_u64 v[34:35], v[34:35], 0, v[36:37]
	v_lshl_add_u64 v[34:35], v[162:163], 2, v[34:35]
	global_load_dword v36, v[34:35], off offset:128
	v_add_u32_e32 v34, v145, v118
	v_ashrrev_i32_e32 v35, 31, v34
	v_lshl_add_u64 v[34:35], v[34:35], 2, s[78:79]
	global_load_dword v34, v[34:35], off
	s_waitcnt vmcnt(0)
	v_fmac_f32_e32 v36, v43, v34
	global_store_dword v[32:33], v36, off offset:128
	s_cbranch_vccnz .LBB0_1235
	s_and_saveexec_b64 s[2:3], s[34:35]
	s_xor_b64 s[2:3], exec, s[2:3]
	v_mov_b32_e32 v109, v163
	v_mov_b32_e32 v32, v58
	v_mov_b32_e32 v33, v163
	s_or_saveexec_b64 s[2:3], s[2:3]
	v_readlane_b32 s8, v254, 2
	v_readlane_b32 s9, v254, 3
	s_nop 1
	v_mov_b64_e32 v[34:35], s[8:9]
	s_xor_b64 exec, exec, s[2:3]
	v_mov_b64_e32 v[34:35], s[0:1]
	v_mov_b64_e32 v[108:109], v[58:59]
	v_mov_b64_e32 v[32:33], v[58:59]
	s_or_b64 exec, exec, s[2:3]
	s_mov_b64 s[2:3], 0

; DI const float* xrow_ptr(const Params& p, int l, int row) {
;   if (l > 0) return p.out + (size_t)row * D;
;   return row < NP ? p.in[0] + (size_t)row * D : p.in[1] + (size_t)(row - NP) * D;
; }
; DI void phase7(const Params& p, int l, unsigned char* smem) {
;     ...
;     foreach_acc(acc, m0, n0, [&](int row, int col, float v) {
;       float xo = xrow_ptr(p, l, row)[col];
;       float gt = mod[(l * 10 + bidx_of(row)) * 3072 + 2048 + col];
;       p.out[(size_t)row * D + col] = xo + gt * v;
;     });
.LBB0_1237:
	v_subrev_u32_e32 v34, s0, v34
	v_and_or_b32 v34, v34, 40, v242
	ds_read_b64 v[34:35], v34
	v_lshlrev_b64 v[36:37], 12, v[108:109]
	v_lshlrev_b64 v[32:33], 12, v[32:33]
	v_lshl_add_u64 v[32:33], v[64:65], 0, v[32:33]
	s_mov_b64 s[2:3], -1
	s_and_b64 vcc, exec, s[6:7]
	s_waitcnt lgkmcnt(0)
	v_lshl_add_u64 v[34:35], v[34:35], 0, v[36:37]
	v_lshl_add_u64 v[34:35], v[162:163], 2, v[34:35]
	global_load_dword v36, v[34:35], off offset:128
	v_add_u32_e32 v34, v146, v118
	v_ashrrev_i32_e32 v35, 31, v34
	v_lshl_add_u64 v[34:35], v[34:35], 2, s[78:79]
	global_load_dword v34, v[34:35], off
	s_waitcnt vmcnt(0)
	v_fmac_f32_e32 v36, v44, v34
	global_store_dword v[32:33], v36, off offset:128
	s_cbranch_vccnz .LBB0_1243
	s_and_saveexec_b64 s[2:3], s[36:37]
	s_xor_b64 s[2:3], exec, s[2:3]
	v_mov_b32_e32 v111, v163
	v_mov_b32_e32 v32, v96
	v_mov_b32_e32 v33, v163
	s_or_saveexec_b64 s[2:3], s[2:3]
	v_readlane_b32 s8, v254, 2
	v_readlane_b32 s9, v254, 3
	s_nop 1
	v_mov_b64_e32 v[34:35], s[8:9]
	s_xor_b64 exec, exec, s[2:3]
	v_mov_b64_e32 v[34:35], s[0:1]
	v_mov_b64_e32 v[110:111], v[96:97]
	v_mov_b64_e32 v[32:33], v[96:97]
	s_or_b64 exec, exec, s[2:3]
	s_mov_b64 s[2:3], 0

; DI const float* xrow_ptr(const Params& p, int l, int row) {
;   if (l > 0) return p.out + (size_t)row * D;
;   return row < NP ? p.in[0] + (size_t)row * D : p.in[1] + (size_t)(row - NP) * D;
; }
; DI void phase7(const Params& p, int l, unsigned char* smem) {
;     ...
;     foreach_acc(acc, m0, n0, [&](int row, int col, float v) {
;       float xo = xrow_ptr(p, l, row)[col];
;       float gt = mod[(l * 10 + bidx_of(row)) * 3072 + 2048 + col];
;       p.out[(size_t)row * D + col] = xo + gt * v;
;     });
.LBB0_1245:
	v_subrev_u32_e32 v34, s0, v34
	v_and_or_b32 v34, v34, 40, v242
	ds_read_b64 v[34:35], v34
	v_lshlrev_b64 v[36:37], 12, v[110:111]
	v_lshlrev_b64 v[32:33], 12, v[32:33]
	v_lshl_add_u64 v[32:33], v[64:65], 0, v[32:33]
	s_mov_b64 s[2:3], -1
	s_and_b64 vcc, exec, s[6:7]
	s_waitcnt lgkmcnt(0)
	v_lshl_add_u64 v[34:35], v[34:35], 0, v[36:37]
	v_lshl_add_u64 v[34:35], v[162:163], 2, v[34:35]
	global_load_dword v36, v[34:35], off offset:128
	v_add_u32_e32 v34, v147, v118
	v_ashrrev_i32_e32 v35, 31, v34
	v_lshl_add_u64 v[34:35], v[34:35], 2, s[78:79]
	global_load_dword v34, v[34:35], off
	s_waitcnt vmcnt(0)
	v_fmac_f32_e32 v36, v45, v34
	global_store_dword v[32:33], v36, off offset:128
	s_cbranch_vccnz .LBB0_1251
	s_and_saveexec_b64 s[2:3], s[38:39]
	s_xor_b64 s[2:3], exec, s[2:3]
	v_mov_b32_e32 v113, v163
	v_mov_b32_e32 v32, v60
	v_mov_b32_e32 v33, v163
	s_or_saveexec_b64 s[2:3], s[2:3]
	v_readlane_b32 s8, v254, 2
	v_readlane_b32 s9, v254, 3
	s_nop 1
	v_mov_b64_e32 v[34:35], s[8:9]
	s_xor_b64 exec, exec, s[2:3]
	v_mov_b64_e32 v[34:35], s[0:1]
	v_mov_b64_e32 v[112:113], v[60:61]
	v_mov_b64_e32 v[32:33], v[60:61]
	s_or_b64 exec, exec, s[2:3]
	s_mov_b64 s[2:3], 0

; DI const float* xrow_ptr(const Params& p, int l, int row) {
;   if (l > 0) return p.out + (size_t)row * D;
;   return row < NP ? p.in[0] + (size_t)row * D : p.in[1] + (size_t)(row - NP) * D;
; }
; DI void phase7(const Params& p, int l, unsigned char* smem) {
;     ...
;     foreach_acc(acc, m0, n0, [&](int row, int col, float v) {
;       float xo = xrow_ptr(p, l, row)[col];
;       float gt = mod[(l * 10 + bidx_of(row)) * 3072 + 2048 + col];
;       p.out[(size_t)row * D + col] = xo + gt * v;
;     });
.LBB0_1253:
	v_subrev_u32_e32 v34, s0, v34
	v_and_or_b32 v34, v34, 40, v242
	ds_read_b64 v[34:35], v34
	v_lshlrev_b64 v[36:37], 12, v[112:113]
	v_lshlrev_b64 v[32:33], 12, v[32:33]
	v_lshl_add_u64 v[32:33], v[64:65], 0, v[32:33]
	s_mov_b64 s[2:3], -1
	s_and_b64 vcc, exec, s[6:7]
	s_waitcnt lgkmcnt(0)
	v_lshl_add_u64 v[34:35], v[34:35], 0, v[36:37]
	v_lshl_add_u64 v[34:35], v[162:163], 2, v[34:35]
	global_load_dword v36, v[34:35], off offset:128
	v_add_u32_e32 v34, v148, v118
	v_ashrrev_i32_e32 v35, 31, v34
	v_lshl_add_u64 v[34:35], v[34:35], 2, s[78:79]
	global_load_dword v34, v[34:35], off
	s_waitcnt vmcnt(0)
	v_fmac_f32_e32 v36, v46, v34
	global_store_dword v[32:33], v36, off offset:128
	s_cbranch_vccnz .LBB0_1259
	s_and_saveexec_b64 s[2:3], s[40:41]
	s_xor_b64 s[2:3], exec, s[2:3]
	v_mov_b32_e32 v63, v163
	v_mov_b32_e32 v32, v102
	v_mov_b32_e32 v33, v163
	s_or_saveexec_b64 s[2:3], s[2:3]
	v_readlane_b32 s8, v254, 2
	v_readlane_b32 s9, v254, 3
	s_nop 1
	v_mov_b64_e32 v[34:35], s[8:9]
	s_xor_b64 exec, exec, s[2:3]
	v_mov_b64_e32 v[34:35], s[0:1]
	v_mov_b64_e32 v[62:63], v[102:103]
	v_mov_b64_e32 v[32:33], v[102:103]
	s_or_b64 exec, exec, s[2:3]
	s_mov_b64 s[2:3], 0

; DI const float* xrow_ptr(const Params& p, int l, int row) {
;   if (l > 0) return p.out + (size_t)row * D;
;   return row < NP ? p.in[0] + (size_t)row * D : p.in[1] + (size_t)(row - NP) * D;
; }
; DI void phase7(const Params& p, int l, unsigned char* smem) {
;     ...
;     foreach_acc(acc, m0, n0, [&](int row, int col, float v) {
;       float xo = xrow_ptr(p, l, row)[col];
;       float gt = mod[(l * 10 + bidx_of(row)) * 3072 + 2048 + col];
;       p.out[(size_t)row * D + col] = xo + gt * v;
;     });
.LBB0_1261:
	v_subrev_u32_e32 v34, s0, v34
	v_and_or_b32 v34, v34, 40, v242
	ds_read_b64 v[34:35], v34
	v_lshlrev_b64 v[36:37], 12, v[62:63]
	v_lshlrev_b64 v[32:33], 12, v[32:33]
	v_lshl_add_u64 v[32:33], v[64:65], 0, v[32:33]
	v_or_b32_e32 v43, 32, v122
	s_mov_b64 s[2:3], -1
	s_and_b64 vcc, exec, s[6:7]
	s_waitcnt lgkmcnt(0)
	v_lshl_add_u64 v[34:35], v[34:35], 0, v[36:37]
	v_lshl_add_u64 v[34:35], v[162:163], 2, v[34:35]
	global_load_dword v36, v[34:35], off offset:128
	v_add_u32_e32 v34, v119, v118
	v_ashrrev_i32_e32 v35, 31, v34
	v_lshl_add_u64 v[34:35], v[34:35], 2, s[78:79]
	global_load_dword v34, v[34:35], off
	s_waitcnt vmcnt(0)
	v_fmac_f32_e32 v36, v47, v34
	global_store_dword v[32:33], v36, off offset:128
	v_or_b32_e32 v32, v43, v123
	v_cmp_lt_i32_e64 s[8:9], s64, v32
	s_cbranch_vccnz .LBB0_1267
	s_and_saveexec_b64 s[2:3], s[8:9]
	s_xor_b64 s[2:3], exec, s[2:3]
	v_mov_b32_e32 v33, v163
	v_add_u32_e32 v36, 0xffffc000, v32
	v_mov_b32_e32 v37, v163
	v_mov_b64_e32 v[34:35], v[32:33]
	s_or_saveexec_b64 s[2:3], s[2:3]
	v_readlane_b32 s8, v254, 2
	v_readlane_b32 s9, v254, 3
	s_nop 1
	v_mov_b64_e32 v[38:39], s[8:9]
	s_xor_b64 exec, exec, s[2:3]
	v_ashrrev_i32_e32 v33, 31, v32
	v_mov_b64_e32 v[38:39], s[0:1]
	v_mov_b64_e32 v[36:37], v[32:33]
	v_mov_b64_e32 v[34:35], v[32:33]
	s_or_b64 exec, exec, s[2:3]
	s_mov_b64 s[2:3], 0

; DI const float* xrow_ptr(const Params& p, int l, int row) {
;   if (l > 0) return p.out + (size_t)row * D;
;   return row < NP ? p.in[0] + (size_t)row * D : p.in[1] + (size_t)(row - NP) * D;
; }
; DI void phase7(const Params& p, int l, unsigned char* smem) {
;     ...
;     foreach_acc(acc, m0, n0, [&](int row, int col, float v) {
;       float xo = xrow_ptr(p, l, row)[col];
;       float gt = mod[(l * 10 + bidx_of(row)) * 3072 + 2048 + col];
;       p.out[(size_t)row * D + col] = xo + gt * v;
;     });
.LBB0_1269:
	v_subrev_u32_e32 v38, s0, v38
	v_and_or_b32 v38, v38, 40, v242
	ds_read_b64 v[38:39], v38
	v_lshlrev_b64 v[36:37], 12, v[36:37]
	v_add_u32_e32 v42, 0xffffc000, v32
	v_cmp_gt_i32_e32 vcc, s50, v32
	v_lshlrev_b64 v[34:35], 12, v[34:35]
	v_lshl_add_u64 v[34:35], v[64:65], 0, v[34:35]
	v_cmp_lt_i32_e64 s[8:9], s64, v32
	s_mov_b64 s[2:3], -1
	s_waitcnt lgkmcnt(0)
	v_lshl_add_u64 v[36:37], v[38:39], 0, v[36:37]
	v_lshl_add_u64 v[36:37], v[162:163], 2, v[36:37]
	global_load_dword v38, v[36:37], off
	v_lshrrev_b32_e32 v36, 4, v42
	v_add_u32_e32 v36, 2, v36
	v_cndmask_b32_e32 v36, v36, v121, vcc
	v_add_u32_e32 v36, s94, v36
	v_mul_lo_u32 v47, v36, s74
	v_add_u32_e32 v36, v47, v120
	v_ashrrev_i32_e32 v37, 31, v36
	v_lshl_add_u64 v[36:37], v[36:37], 2, s[78:79]
	global_load_dword v36, v[36:37], off
	s_and_b64 vcc, exec, s[6:7]
	s_waitcnt vmcnt(0)
	v_fmac_f32_e32 v38, v16, v36
	global_store_dword v[34:35], v38, off
	v_or_b32_e32 v34, v43, v124
	v_cmp_lt_i32_e64 s[10:11], s64, v34
	s_cbranch_vccnz .LBB0_1275
	s_and_saveexec_b64 s[2:3], s[10:11]
	s_xor_b64 s[2:3], exec, s[2:3]
	v_mov_b32_e32 v35, v163
	v_add_u32_e32 v38, 0xffffc000, v34
	v_mov_b32_e32 v39, v163
	v_mov_b64_e32 v[36:37], v[34:35]
	s_or_saveexec_b64 s[2:3], s[2:3]
	v_readlane_b32 s10, v254, 2
	v_readlane_b32 s11, v254, 3
	s_nop 1
	v_mov_b64_e32 v[40:41], s[10:11]
	s_xor_b64 exec, exec, s[2:3]
	v_ashrrev_i32_e32 v35, 31, v34
	v_mov_b64_e32 v[40:41], s[0:1]
	v_mov_b64_e32 v[38:39], v[34:35]
	v_mov_b64_e32 v[36:37], v[34:35]
	s_or_b64 exec, exec, s[2:3]
	s_mov_b64 s[2:3], 0

; DI const float* xrow_ptr(const Params& p, int l, int row) {
;   if (l > 0) return p.out + (size_t)row * D;
;   return row < NP ? p.in[0] + (size_t)row * D : p.in[1] + (size_t)(row - NP) * D;
; }
; DI void phase7(const Params& p, int l, unsigned char* smem) {
;     ...
;     foreach_acc(acc, m0, n0, [&](int row, int col, float v) {
;       float xo = xrow_ptr(p, l, row)[col];
;       float gt = mod[(l * 10 + bidx_of(row)) * 3072 + 2048 + col];
;       p.out[(size_t)row * D + col] = xo + gt * v;
;     });
.LBB0_1277:
	v_subrev_u32_e32 v40, s0, v40
	v_and_or_b32 v40, v40, 40, v242
	ds_read_b64 v[40:41], v40
	v_add_u32_e32 v46, 0xffffc000, v34
	v_lshrrev_b32_e32 v16, 4, v46
	v_cmp_gt_i32_e32 vcc, s50, v34
	v_add_u32_e32 v16, 2, v16
	v_lshlrev_b64 v[38:39], 12, v[38:39]
	v_cndmask_b32_e32 v16, v16, v121, vcc
	v_add_u32_e32 v16, s94, v16
	v_mul_lo_u32 v49, v16, s74
	v_cmp_lt_i32_e64 s[10:11], s64, v34
	s_mov_b64 s[2:3], -1
	s_and_b64 vcc, exec, s[6:7]
	s_waitcnt lgkmcnt(0)
	v_lshl_add_u64 v[38:39], v[40:41], 0, v[38:39]
	v_lshl_add_u64 v[38:39], v[162:163], 2, v[38:39]
	global_load_dword v40, v[38:39], off
	v_add_u32_e32 v38, v49, v120
	v_ashrrev_i32_e32 v39, 31, v38
	v_lshl_add_u64 v[38:39], v[38:39], 2, s[78:79]
	global_load_dword v16, v[38:39], off
	s_waitcnt vmcnt(0)
	v_fmac_f32_e32 v40, v17, v16
	v_lshlrev_b64 v[16:17], 12, v[36:37]
	v_lshl_add_u64 v[16:17], v[64:65], 0, v[16:17]
	global_store_dword v[16:17], v40, off
	v_or_b32_e32 v16, v43, v125
	v_cmp_lt_i32_e64 s[12:13], s64, v16
	s_cbranch_vccnz .LBB0_1283
	s_and_saveexec_b64 s[2:3], s[12:13]
	s_xor_b64 s[2:3], exec, s[2:3]
	v_mov_b32_e32 v17, v163
	v_add_u32_e32 v38, 0xffffc000, v16
	v_mov_b32_e32 v39, v163
	v_mov_b64_e32 v[36:37], v[16:17]
	s_or_saveexec_b64 s[2:3], s[2:3]
	v_readlane_b32 s12, v254, 2
	v_readlane_b32 s13, v254, 3
	s_nop 1
	v_mov_b64_e32 v[40:41], s[12:13]
	s_xor_b64 exec, exec, s[2:3]
	v_ashrrev_i32_e32 v17, 31, v16
	v_mov_b64_e32 v[40:41], s[0:1]
	v_mov_b64_e32 v[38:39], v[16:17]
	v_mov_b64_e32 v[36:37], v[16:17]
	s_or_b64 exec, exec, s[2:3]
	s_mov_b64 s[2:3], 0

; DI const float* xrow_ptr(const Params& p, int l, int row) {
;   if (l > 0) return p.out + (size_t)row * D;
;   return row < NP ? p.in[0] + (size_t)row * D : p.in[1] + (size_t)(row - NP) * D;
; }
; DI void phase7(const Params& p, int l, unsigned char* smem) {
;     ...
;     foreach_acc(acc, m0, n0, [&](int row, int col, float v) {
;       float xo = xrow_ptr(p, l, row)[col];
;       float gt = mod[(l * 10 + bidx_of(row)) * 3072 + 2048 + col];
;       p.out[(size_t)row * D + col] = xo + gt * v;
;     });
.LBB0_1285:
	v_subrev_u32_e32 v40, s0, v40
	v_and_or_b32 v40, v40, 40, v242
	ds_read_b64 v[40:41], v40
	v_lshlrev_b64 v[38:39], 12, v[38:39]
	v_add_u32_e32 v48, 0xffffc000, v16
	v_cmp_gt_i32_e32 vcc, s50, v16
	v_lshlrev_b64 v[36:37], 12, v[36:37]
	v_lshl_add_u64 v[36:37], v[64:65], 0, v[36:37]
	v_cmp_lt_i32_e64 s[12:13], s64, v16
	s_mov_b64 s[2:3], -1
	s_waitcnt lgkmcnt(0)
	v_lshl_add_u64 v[38:39], v[40:41], 0, v[38:39]
	v_lshl_add_u64 v[38:39], v[162:163], 2, v[38:39]
	global_load_dword v40, v[38:39], off
	v_lshrrev_b32_e32 v38, 4, v48
	v_add_u32_e32 v38, 2, v38
	v_cndmask_b32_e32 v38, v38, v121, vcc
	v_add_u32_e32 v38, s94, v38
	v_mul_lo_u32 v53, v38, s74
	v_add_u32_e32 v38, v53, v120
	v_ashrrev_i32_e32 v39, 31, v38
	v_lshl_add_u64 v[38:39], v[38:39], 2, s[78:79]
	global_load_dword v38, v[38:39], off
	s_and_b64 vcc, exec, s[6:7]
	s_waitcnt vmcnt(0)
	v_fmac_f32_e32 v40, v18, v38
	global_store_dword v[36:37], v40, off
	v_or_b32_e32 v36, v43, v126
	v_cmp_lt_i32_e64 s[14:15], s64, v36
	s_cbranch_vccnz .LBB0_1291
	s_and_saveexec_b64 s[2:3], s[14:15]
	s_xor_b64 s[2:3], exec, s[2:3]
	v_mov_b32_e32 v37, v163
	v_add_u32_e32 v40, 0xffffc000, v36
	v_mov_b32_e32 v41, v163
	v_mov_b64_e32 v[38:39], v[36:37]
	s_or_saveexec_b64 s[2:3], s[2:3]
	v_readlane_b32 s14, v254, 2
	v_readlane_b32 s15, v254, 3
	s_nop 1
	v_mov_b64_e32 v[44:45], s[14:15]
	s_xor_b64 exec, exec, s[2:3]
	v_ashrrev_i32_e32 v37, 31, v36
	v_mov_b64_e32 v[44:45], s[0:1]
	v_mov_b64_e32 v[40:41], v[36:37]
	v_mov_b64_e32 v[38:39], v[36:37]
	s_or_b64 exec, exec, s[2:3]
	s_mov_b64 s[2:3], 0

; DI const float* xrow_ptr(const Params& p, int l, int row) {
;   if (l > 0) return p.out + (size_t)row * D;
;   return row < NP ? p.in[0] + (size_t)row * D : p.in[1] + (size_t)(row - NP) * D;
; }
; DI void phase7(const Params& p, int l, unsigned char* smem) {
;     ...
;     foreach_acc(acc, m0, n0, [&](int row, int col, float v) {
;       float xo = xrow_ptr(p, l, row)[col];
;       float gt = mod[(l * 10 + bidx_of(row)) * 3072 + 2048 + col];
;       p.out[(size_t)row * D + col] = xo + gt * v;
;     });
.LBB0_1293:
	v_subrev_u32_e32 v44, s0, v44
	v_and_or_b32 v44, v44, 40, v242
	ds_read_b64 v[44:45], v44
	v_add_u32_e32 v52, 0xffffc000, v36
	v_lshrrev_b32_e32 v18, 4, v52
	v_cmp_gt_i32_e32 vcc, s50, v36
	v_add_u32_e32 v18, 2, v18
	v_lshlrev_b64 v[40:41], 12, v[40:41]
	v_cndmask_b32_e32 v18, v18, v121, vcc
	v_add_u32_e32 v18, s94, v18
	v_mul_lo_u32 v55, v18, s74
	v_cmp_lt_i32_e64 s[14:15], s64, v36
	s_mov_b64 s[2:3], -1
	s_and_b64 vcc, exec, s[6:7]
	s_waitcnt lgkmcnt(0)
	v_lshl_add_u64 v[40:41], v[44:45], 0, v[40:41]
	v_lshl_add_u64 v[40:41], v[162:163], 2, v[40:41]
	global_load_dword v44, v[40:41], off
	v_add_u32_e32 v40, v55, v120
	v_ashrrev_i32_e32 v41, 31, v40
	v_lshl_add_u64 v[40:41], v[40:41], 2, s[78:79]
	global_load_dword v18, v[40:41], off
	s_waitcnt vmcnt(0)
	v_fmac_f32_e32 v44, v19, v18
	v_lshlrev_b64 v[18:19], 12, v[38:39]
	v_lshl_add_u64 v[18:19], v[64:65], 0, v[18:19]
	global_store_dword v[18:19], v44, off
	v_or_b32_e32 v18, v43, v127
	v_cmp_lt_i32_e64 s[16:17], s64, v18
	s_cbranch_vccnz .LBB0_1299
	s_and_saveexec_b64 s[2:3], s[16:17]
	s_xor_b64 s[2:3], exec, s[2:3]
	v_mov_b32_e32 v19, v163
	v_add_u32_e32 v40, 0xffffc000, v18
	v_mov_b32_e32 v41, v163
	v_mov_b64_e32 v[38:39], v[18:19]
	s_or_saveexec_b64 s[2:3], s[2:3]
	v_readlane_b32 s16, v254, 2
	v_readlane_b32 s17, v254, 3
	s_nop 1
	v_mov_b64_e32 v[44:45], s[16:17]
	s_xor_b64 exec, exec, s[2:3]
	v_ashrrev_i32_e32 v19, 31, v18
	v_mov_b64_e32 v[44:45], s[0:1]
	v_mov_b64_e32 v[40:41], v[18:19]
	v_mov_b64_e32 v[38:39], v[18:19]
	s_or_b64 exec, exec, s[2:3]
	s_mov_b64 s[2:3], 0

; DI const float* xrow_ptr(const Params& p, int l, int row) {
;   if (l > 0) return p.out + (size_t)row * D;
;   return row < NP ? p.in[0] + (size_t)row * D : p.in[1] + (size_t)(row - NP) * D;
; }
; DI void phase7(const Params& p, int l, unsigned char* smem) {
;     ...
;     foreach_acc(acc, m0, n0, [&](int row, int col, float v) {
;       float xo = xrow_ptr(p, l, row)[col];
;       float gt = mod[(l * 10 + bidx_of(row)) * 3072 + 2048 + col];
;       p.out[(size_t)row * D + col] = xo + gt * v;
;     });
.LBB0_1301:
	v_subrev_u32_e32 v44, s0, v44
	v_and_or_b32 v44, v44, 40, v242
	ds_read_b64 v[44:45], v44
	v_lshlrev_b64 v[40:41], 12, v[40:41]
	v_add_u32_e32 v54, 0xffffc000, v18
	v_cmp_gt_i32_e32 vcc, s50, v18
	v_lshlrev_b64 v[38:39], 12, v[38:39]
	v_lshl_add_u64 v[38:39], v[64:65], 0, v[38:39]
	v_cmp_lt_i32_e64 s[16:17], s64, v18
	s_mov_b64 s[2:3], -1
	s_waitcnt lgkmcnt(0)
	v_lshl_add_u64 v[40:41], v[44:45], 0, v[40:41]
	v_lshl_add_u64 v[40:41], v[162:163], 2, v[40:41]
	global_load_dword v44, v[40:41], off
	v_lshrrev_b32_e32 v40, 4, v54
	v_add_u32_e32 v40, 2, v40
	v_cndmask_b32_e32 v40, v40, v121, vcc
	v_add_u32_e32 v40, s94, v40
	v_mul_lo_u32 v57, v40, s74
	v_add_u32_e32 v40, v57, v120
	v_ashrrev_i32_e32 v41, 31, v40
	v_lshl_add_u64 v[40:41], v[40:41], 2, s[78:79]
	global_load_dword v40, v[40:41], off
	s_and_b64 vcc, exec, s[6:7]
	s_waitcnt vmcnt(0)
	v_fmac_f32_e32 v44, v20, v40
	global_store_dword v[38:39], v44, off
	v_or_b32_e32 v38, v43, v128
	v_cmp_lt_i32_e64 s[18:19], s64, v38
	s_cbranch_vccnz .LBB0_1307
	s_and_saveexec_b64 s[2:3], s[18:19]
	s_xor_b64 s[2:3], exec, s[2:3]
	v_mov_b32_e32 v39, v163
	v_add_u32_e32 v44, 0xffffc000, v38
	v_mov_b32_e32 v45, v163
	v_mov_b64_e32 v[40:41], v[38:39]
	s_or_saveexec_b64 s[2:3], s[2:3]
	v_readlane_b32 s18, v254, 2
	v_readlane_b32 s19, v254, 3
	s_nop 1
	v_mov_b64_e32 v[50:51], s[18:19]
	s_xor_b64 exec, exec, s[2:3]
	v_ashrrev_i32_e32 v39, 31, v38
	v_mov_b64_e32 v[50:51], s[0:1]
	v_mov_b64_e32 v[44:45], v[38:39]
	v_mov_b64_e32 v[40:41], v[38:39]
	s_or_b64 exec, exec, s[2:3]
	s_mov_b64 s[2:3], 0

; DI const float* xrow_ptr(const Params& p, int l, int row) {
;   if (l > 0) return p.out + (size_t)row * D;
;   return row < NP ? p.in[0] + (size_t)row * D : p.in[1] + (size_t)(row - NP) * D;
; }
; DI void phase7(const Params& p, int l, unsigned char* smem) {
;     ...
;     foreach_acc(acc, m0, n0, [&](int row, int col, float v) {
;       float xo = xrow_ptr(p, l, row)[col];
;       float gt = mod[(l * 10 + bidx_of(row)) * 3072 + 2048 + col];
;       p.out[(size_t)row * D + col] = xo + gt * v;
;     });
.LBB0_1309:
	v_subrev_u32_e32 v50, s0, v50
	v_and_or_b32 v50, v50, 40, v242
	ds_read_b64 v[50:51], v50
	v_add_u32_e32 v56, 0xffffc000, v38
	v_lshrrev_b32_e32 v20, 4, v56
	v_cmp_gt_i32_e32 vcc, s50, v38
	v_add_u32_e32 v20, 2, v20
	v_lshlrev_b64 v[44:45], 12, v[44:45]
	v_cndmask_b32_e32 v20, v20, v121, vcc
	v_add_u32_e32 v20, s94, v20
	v_mul_lo_u32 v61, v20, s74
	v_cmp_lt_i32_e64 s[18:19], s64, v38
	s_mov_b64 s[2:3], -1
	s_and_b64 vcc, exec, s[6:7]
	s_waitcnt lgkmcnt(0)
	v_lshl_add_u64 v[44:45], v[50:51], 0, v[44:45]
	v_lshl_add_u64 v[44:45], v[162:163], 2, v[44:45]
	global_load_dword v50, v[44:45], off
	v_add_u32_e32 v44, v61, v120
	v_ashrrev_i32_e32 v45, 31, v44
	v_lshl_add_u64 v[44:45], v[44:45], 2, s[78:79]
	global_load_dword v20, v[44:45], off
	s_waitcnt vmcnt(0)
	v_fmac_f32_e32 v50, v21, v20
	v_lshlrev_b64 v[20:21], 12, v[40:41]
	v_lshl_add_u64 v[20:21], v[64:65], 0, v[20:21]
	global_store_dword v[20:21], v50, off
	v_or_b32_e32 v20, v43, v129
	v_cmp_lt_i32_e64 s[20:21], s64, v20
	s_cbranch_vccnz .LBB0_1315
	s_and_saveexec_b64 s[2:3], s[20:21]
	s_xor_b64 s[2:3], exec, s[2:3]
	v_mov_b32_e32 v21, v163
	v_add_u32_e32 v44, 0xffffc000, v20
	v_mov_b32_e32 v45, v163
	v_mov_b64_e32 v[40:41], v[20:21]
	s_or_saveexec_b64 s[2:3], s[2:3]
	v_readlane_b32 s20, v254, 2
	v_readlane_b32 s21, v254, 3
	s_nop 1
	v_mov_b64_e32 v[50:51], s[20:21]
	s_xor_b64 exec, exec, s[2:3]
	v_ashrrev_i32_e32 v21, 31, v20
	v_mov_b64_e32 v[50:51], s[0:1]
	v_mov_b64_e32 v[44:45], v[20:21]
	v_mov_b64_e32 v[40:41], v[20:21]
	s_or_b64 exec, exec, s[2:3]
	s_mov_b64 s[2:3], 0

; DI const float* xrow_ptr(const Params& p, int l, int row) {
;   if (l > 0) return p.out + (size_t)row * D;
;   return row < NP ? p.in[0] + (size_t)row * D : p.in[1] + (size_t)(row - NP) * D;
; }
; DI void phase7(const Params& p, int l, unsigned char* smem) {
;     ...
;     foreach_acc(acc, m0, n0, [&](int row, int col, float v) {
;       float xo = xrow_ptr(p, l, row)[col];
;       float gt = mod[(l * 10 + bidx_of(row)) * 3072 + 2048 + col];
;       p.out[(size_t)row * D + col] = xo + gt * v;
;     });
.LBB0_1317:
	v_subrev_u32_e32 v50, s0, v50
	v_and_or_b32 v50, v50, 40, v242
	ds_read_b64 v[50:51], v50
	v_lshlrev_b64 v[44:45], 12, v[44:45]
	v_add_u32_e32 v60, 0xffffc000, v20
	v_cmp_gt_i32_e32 vcc, s50, v20
	v_lshlrev_b64 v[40:41], 12, v[40:41]
	v_lshl_add_u64 v[40:41], v[64:65], 0, v[40:41]
	v_cmp_lt_i32_e64 s[20:21], s64, v20
	s_mov_b64 s[2:3], -1
	s_waitcnt lgkmcnt(0)
	v_lshl_add_u64 v[44:45], v[50:51], 0, v[44:45]
	v_lshl_add_u64 v[44:45], v[162:163], 2, v[44:45]
	global_load_dword v50, v[44:45], off
	v_lshrrev_b32_e32 v44, 4, v60
	v_add_u32_e32 v44, 2, v44
	v_cndmask_b32_e32 v44, v44, v121, vcc
	v_add_u32_e32 v44, s94, v44
	v_mul_lo_u32 v63, v44, s74
	v_add_u32_e32 v44, v63, v120
	v_ashrrev_i32_e32 v45, 31, v44
	v_lshl_add_u64 v[44:45], v[44:45], 2, s[78:79]
	global_load_dword v44, v[44:45], off
	s_and_b64 vcc, exec, s[6:7]
	s_waitcnt vmcnt(0)
	v_fmac_f32_e32 v50, v22, v44
	global_store_dword v[40:41], v50, off
	v_or_b32_e32 v40, v43, v130
	v_cmp_lt_i32_e64 s[22:23], s64, v40
	s_cbranch_vccnz .LBB0_1323
	s_and_saveexec_b64 s[2:3], s[22:23]
	s_xor_b64 s[2:3], exec, s[2:3]
	v_mov_b32_e32 v41, v163
	v_add_u32_e32 v50, 0xffffc000, v40
	v_mov_b32_e32 v51, v163
	v_mov_b64_e32 v[44:45], v[40:41]
	s_or_saveexec_b64 s[2:3], s[2:3]
	v_readlane_b32 s22, v254, 2
	v_readlane_b32 s23, v254, 3
	s_nop 1
	v_mov_b64_e32 v[58:59], s[22:23]
	s_xor_b64 exec, exec, s[2:3]
	v_ashrrev_i32_e32 v41, 31, v40
	v_mov_b64_e32 v[58:59], s[0:1]
	v_mov_b64_e32 v[50:51], v[40:41]
	v_mov_b64_e32 v[44:45], v[40:41]
	s_or_b64 exec, exec, s[2:3]
	s_mov_b64 s[2:3], 0

; DI const float* xrow_ptr(const Params& p, int l, int row) {
;   if (l > 0) return p.out + (size_t)row * D;
;   return row < NP ? p.in[0] + (size_t)row * D : p.in[1] + (size_t)(row - NP) * D;
; }
; DI void phase7(const Params& p, int l, unsigned char* smem) {
;     ...
;     foreach_acc(acc, m0, n0, [&](int row, int col, float v) {
;       float xo = xrow_ptr(p, l, row)[col];
;       float gt = mod[(l * 10 + bidx_of(row)) * 3072 + 2048 + col];
;       p.out[(size_t)row * D + col] = xo + gt * v;
;     });
.LBB0_1325:
	v_subrev_u32_e32 v58, s0, v58
	v_and_or_b32 v58, v58, 40, v242
	ds_read_b64 v[58:59], v58
	v_add_u32_e32 v62, 0xffffc000, v40
	v_lshrrev_b32_e32 v22, 4, v62
	v_cmp_gt_i32_e32 vcc, s50, v40
	v_add_u32_e32 v22, 2, v22
	v_lshlrev_b64 v[50:51], 12, v[50:51]
	v_cndmask_b32_e32 v22, v22, v121, vcc
	v_add_u32_e32 v22, s94, v22
	v_mul_lo_u32 v67, v22, s74
	v_cmp_lt_i32_e64 s[22:23], s64, v40
	s_mov_b64 s[2:3], -1
	s_and_b64 vcc, exec, s[6:7]
	s_waitcnt lgkmcnt(0)
	v_lshl_add_u64 v[50:51], v[58:59], 0, v[50:51]
	v_lshl_add_u64 v[50:51], v[162:163], 2, v[50:51]
	global_load_dword v58, v[50:51], off
	v_add_u32_e32 v50, v67, v120
	v_ashrrev_i32_e32 v51, 31, v50
	v_lshl_add_u64 v[50:51], v[50:51], 2, s[78:79]
	global_load_dword v22, v[50:51], off
	s_waitcnt vmcnt(0)
	v_fmac_f32_e32 v58, v23, v22
	v_lshlrev_b64 v[22:23], 12, v[44:45]
	v_lshl_add_u64 v[22:23], v[64:65], 0, v[22:23]
	global_store_dword v[22:23], v58, off
	v_or_b32_e32 v22, v43, v131
	v_cmp_lt_i32_e64 s[24:25], s64, v22
	s_cbranch_vccnz .LBB0_1331
	s_and_saveexec_b64 s[2:3], s[24:25]
	s_xor_b64 s[2:3], exec, s[2:3]
	v_mov_b32_e32 v23, v163
	v_add_u32_e32 v50, 0xffffc000, v22
	v_mov_b32_e32 v51, v163
	v_mov_b64_e32 v[44:45], v[22:23]
	s_or_saveexec_b64 s[2:3], s[2:3]
	v_readlane_b32 s24, v254, 2
	v_readlane_b32 s25, v254, 3
	s_nop 1
	v_mov_b64_e32 v[58:59], s[24:25]
	s_xor_b64 exec, exec, s[2:3]
	v_ashrrev_i32_e32 v23, 31, v22
	v_mov_b64_e32 v[58:59], s[0:1]
	v_mov_b64_e32 v[50:51], v[22:23]
	v_mov_b64_e32 v[44:45], v[22:23]
	s_or_b64 exec, exec, s[2:3]
	s_mov_b64 s[2:3], 0

; DI const float* xrow_ptr(const Params& p, int l, int row) {
;   if (l > 0) return p.out + (size_t)row * D;
;   return row < NP ? p.in[0] + (size_t)row * D : p.in[1] + (size_t)(row - NP) * D;
; }
; DI void phase7(const Params& p, int l, unsigned char* smem) {
;     ...
;     foreach_acc(acc, m0, n0, [&](int row, int col, float v) {
;       float xo = xrow_ptr(p, l, row)[col];
;       float gt = mod[(l * 10 + bidx_of(row)) * 3072 + 2048 + col];
;       p.out[(size_t)row * D + col] = xo + gt * v;
;     });
.LBB0_1333:
	v_subrev_u32_e32 v58, s0, v58
	v_and_or_b32 v58, v58, 40, v242
	ds_read_b64 v[58:59], v58
	v_lshlrev_b64 v[50:51], 12, v[50:51]
	v_add_u32_e32 v66, 0xffffc000, v22
	v_cmp_gt_i32_e32 vcc, s50, v22
	v_lshlrev_b64 v[44:45], 12, v[44:45]
	v_lshl_add_u64 v[44:45], v[64:65], 0, v[44:45]
	v_cmp_lt_i32_e64 s[24:25], s64, v22
	s_mov_b64 s[2:3], -1
	s_waitcnt lgkmcnt(0)
	v_lshl_add_u64 v[50:51], v[58:59], 0, v[50:51]
	v_lshl_add_u64 v[50:51], v[162:163], 2, v[50:51]
	global_load_dword v58, v[50:51], off
	v_lshrrev_b32_e32 v50, 4, v66
	v_add_u32_e32 v50, 2, v50
	v_cndmask_b32_e32 v50, v50, v121, vcc
	v_add_u32_e32 v50, s94, v50
	v_mul_lo_u32 v71, v50, s74
	v_add_u32_e32 v50, v71, v120
	v_ashrrev_i32_e32 v51, 31, v50
	v_lshl_add_u64 v[50:51], v[50:51], 2, s[78:79]
	global_load_dword v50, v[50:51], off
	s_and_b64 vcc, exec, s[6:7]
	s_waitcnt vmcnt(0)
	v_fmac_f32_e32 v58, v24, v50
	global_store_dword v[44:45], v58, off
	v_or_b32_e32 v44, v43, v132
	v_cmp_lt_i32_e64 s[26:27], s64, v44
	s_cbranch_vccnz .LBB0_1339
	s_and_saveexec_b64 s[2:3], s[26:27]
	s_xor_b64 s[2:3], exec, s[2:3]
	v_mov_b32_e32 v45, v163
	v_add_u32_e32 v58, 0xffffc000, v44
	v_mov_b32_e32 v59, v163
	v_mov_b64_e32 v[50:51], v[44:45]
	s_or_saveexec_b64 s[2:3], s[2:3]
	v_readlane_b32 s26, v254, 2
	v_readlane_b32 s27, v254, 3
	s_nop 1
	v_mov_b64_e32 v[68:69], s[26:27]
	s_xor_b64 exec, exec, s[2:3]
	v_ashrrev_i32_e32 v45, 31, v44
	v_mov_b64_e32 v[68:69], s[0:1]
	v_mov_b64_e32 v[58:59], v[44:45]
	v_mov_b64_e32 v[50:51], v[44:45]
	s_or_b64 exec, exec, s[2:3]
	s_mov_b64 s[2:3], 0

; DI const float* xrow_ptr(const Params& p, int l, int row) {
;   if (l > 0) return p.out + (size_t)row * D;
;   return row < NP ? p.in[0] + (size_t)row * D : p.in[1] + (size_t)(row - NP) * D;
; }
; DI void phase7(const Params& p, int l, unsigned char* smem) {
;     ...
;     foreach_acc(acc, m0, n0, [&](int row, int col, float v) {
;       float xo = xrow_ptr(p, l, row)[col];
;       float gt = mod[(l * 10 + bidx_of(row)) * 3072 + 2048 + col];
;       p.out[(size_t)row * D + col] = xo + gt * v;
;     });
.LBB0_1341:
	v_subrev_u32_e32 v68, s0, v68
	v_and_or_b32 v68, v68, 40, v242
	ds_read_b64 v[68:69], v68
	v_add_u32_e32 v70, 0xffffc000, v44
	v_lshrrev_b32_e32 v24, 4, v70
	v_cmp_gt_i32_e32 vcc, s50, v44
	v_add_u32_e32 v24, 2, v24
	v_lshlrev_b64 v[58:59], 12, v[58:59]
	v_cndmask_b32_e32 v24, v24, v121, vcc
	v_add_u32_e32 v24, s94, v24
	v_mul_lo_u32 v73, v24, s74
	v_cmp_lt_i32_e64 s[26:27], s64, v44
	s_mov_b64 s[2:3], -1
	s_and_b64 vcc, exec, s[6:7]
	s_waitcnt lgkmcnt(0)
	v_lshl_add_u64 v[58:59], v[68:69], 0, v[58:59]
	v_lshl_add_u64 v[58:59], v[162:163], 2, v[58:59]
	global_load_dword v68, v[58:59], off
	v_add_u32_e32 v58, v73, v120
	v_ashrrev_i32_e32 v59, 31, v58
	v_lshl_add_u64 v[58:59], v[58:59], 2, s[78:79]
	global_load_dword v24, v[58:59], off
	s_waitcnt vmcnt(0)
	v_fmac_f32_e32 v68, v25, v24
	v_lshlrev_b64 v[24:25], 12, v[50:51]
	v_lshl_add_u64 v[24:25], v[64:65], 0, v[24:25]
	global_store_dword v[24:25], v68, off
	v_or_b32_e32 v24, v43, v133
	v_cmp_lt_i32_e64 s[28:29], s64, v24
	s_cbranch_vccnz .LBB0_1347
	s_and_saveexec_b64 s[2:3], s[28:29]
	s_xor_b64 s[2:3], exec, s[2:3]
	v_mov_b32_e32 v25, v163
	v_add_u32_e32 v58, 0xffffc000, v24
	v_mov_b32_e32 v59, v163
	v_mov_b64_e32 v[50:51], v[24:25]
	s_or_saveexec_b64 s[2:3], s[2:3]
	v_readlane_b32 s28, v254, 2
	v_readlane_b32 s29, v254, 3
	s_nop 1
	v_mov_b64_e32 v[68:69], s[28:29]
	s_xor_b64 exec, exec, s[2:3]
	v_ashrrev_i32_e32 v25, 31, v24
	v_mov_b64_e32 v[68:69], s[0:1]
	v_mov_b64_e32 v[58:59], v[24:25]
	v_mov_b64_e32 v[50:51], v[24:25]
	s_or_b64 exec, exec, s[2:3]
	s_mov_b64 s[2:3], 0

; DI const float* xrow_ptr(const Params& p, int l, int row) {
;   if (l > 0) return p.out + (size_t)row * D;
;   return row < NP ? p.in[0] + (size_t)row * D : p.in[1] + (size_t)(row - NP) * D;
; }
; DI void phase7(const Params& p, int l, unsigned char* smem) {
;     ...
;     foreach_acc(acc, m0, n0, [&](int row, int col, float v) {
;       float xo = xrow_ptr(p, l, row)[col];
;       float gt = mod[(l * 10 + bidx_of(row)) * 3072 + 2048 + col];
;       p.out[(size_t)row * D + col] = xo + gt * v;
;     });
.LBB0_1349:
	v_subrev_u32_e32 v68, s0, v68
	v_and_or_b32 v68, v68, 40, v242
	ds_read_b64 v[68:69], v68
	v_lshlrev_b64 v[58:59], 12, v[58:59]
	v_add_u32_e32 v72, 0xffffc000, v24
	v_cmp_gt_i32_e32 vcc, s50, v24
	v_lshlrev_b64 v[50:51], 12, v[50:51]
	v_lshl_add_u64 v[50:51], v[64:65], 0, v[50:51]
	v_cmp_lt_i32_e64 s[28:29], s64, v24
	s_mov_b64 s[2:3], -1
	s_waitcnt lgkmcnt(0)
	v_lshl_add_u64 v[58:59], v[68:69], 0, v[58:59]
	v_lshl_add_u64 v[58:59], v[162:163], 2, v[58:59]
	global_load_dword v68, v[58:59], off
	v_lshrrev_b32_e32 v58, 4, v72
	v_add_u32_e32 v58, 2, v58
	v_cndmask_b32_e32 v58, v58, v121, vcc
	v_add_u32_e32 v58, s94, v58
	v_mul_lo_u32 v88, v58, s74
	v_add_u32_e32 v58, v88, v120
	v_ashrrev_i32_e32 v59, 31, v58
	v_lshl_add_u64 v[58:59], v[58:59], 2, s[78:79]
	global_load_dword v58, v[58:59], off
	s_and_b64 vcc, exec, s[6:7]
	s_waitcnt vmcnt(0)
	v_fmac_f32_e32 v68, v26, v58
	global_store_dword v[50:51], v68, off
	v_or_b32_e32 v50, v43, v134
	v_cmp_lt_i32_e64 s[30:31], s64, v50
	s_cbranch_vccnz .LBB0_1355
	s_and_saveexec_b64 s[2:3], s[30:31]
	s_xor_b64 s[2:3], exec, s[2:3]
	v_mov_b32_e32 v51, v163
	v_add_u32_e32 v68, 0xffffc000, v50
	v_mov_b32_e32 v69, v163
	v_mov_b64_e32 v[58:59], v[50:51]
	s_or_saveexec_b64 s[2:3], s[2:3]
	v_readlane_b32 s30, v254, 2
	v_readlane_b32 s31, v254, 3
	s_nop 1
	v_mov_b64_e32 v[74:75], s[30:31]
	s_xor_b64 exec, exec, s[2:3]
	v_ashrrev_i32_e32 v51, 31, v50
	v_mov_b64_e32 v[74:75], s[0:1]
	v_mov_b64_e32 v[68:69], v[50:51]
	v_mov_b64_e32 v[58:59], v[50:51]
	s_or_b64 exec, exec, s[2:3]
	s_mov_b64 s[2:3], 0

; DI const float* xrow_ptr(const Params& p, int l, int row) {
;   if (l > 0) return p.out + (size_t)row * D;
;   return row < NP ? p.in[0] + (size_t)row * D : p.in[1] + (size_t)(row - NP) * D;
; }
; DI void phase7(const Params& p, int l, unsigned char* smem) {
;     ...
;     foreach_acc(acc, m0, n0, [&](int row, int col, float v) {
;       float xo = xrow_ptr(p, l, row)[col];
;       float gt = mod[(l * 10 + bidx_of(row)) * 3072 + 2048 + col];
;       p.out[(size_t)row * D + col] = xo + gt * v;
;     });
.LBB0_1357:
	v_subrev_u32_e32 v74, s0, v74
	v_and_or_b32 v74, v74, 40, v242
	ds_read_b64 v[74:75], v74
	v_lshlrev_b64 v[68:69], 12, v[68:69]
	v_cmp_gt_i32_e32 vcc, s50, v50
	v_cmp_lt_i32_e64 s[30:31], s64, v50
	s_mov_b64 s[2:3], -1
	s_waitcnt lgkmcnt(0)
	v_lshl_add_u64 v[68:69], v[74:75], 0, v[68:69]
	v_add_u32_e32 v74, 0xffffc000, v50
	v_lshrrev_b32_e32 v26, 4, v74
	v_add_u32_e32 v26, 2, v26
	v_cndmask_b32_e32 v26, v26, v121, vcc
	v_add_u32_e32 v26, s94, v26
	v_lshl_add_u64 v[68:69], v[162:163], 2, v[68:69]
	v_mul_lo_u32 v89, v26, s74
	global_load_dword v75, v[68:69], off
	v_add_u32_e32 v68, v89, v120
	v_ashrrev_i32_e32 v69, 31, v68
	v_lshl_add_u64 v[68:69], v[68:69], 2, s[78:79]
	global_load_dword v26, v[68:69], off
	s_and_b64 vcc, exec, s[6:7]
	s_waitcnt vmcnt(0)
	v_fmac_f32_e32 v75, v27, v26
	v_lshlrev_b64 v[26:27], 12, v[58:59]
	v_lshl_add_u64 v[26:27], v[64:65], 0, v[26:27]
	global_store_dword v[26:27], v75, off
	v_or_b32_e32 v26, v43, v135
	v_cmp_lt_i32_e64 s[34:35], s64, v26
	s_cbranch_vccnz .LBB0_1363
	s_and_saveexec_b64 s[2:3], s[34:35]
	s_xor_b64 s[2:3], exec, s[2:3]
	v_mov_b32_e32 v27, v163
	v_add_u32_e32 v68, 0xffffc000, v26
	v_mov_b32_e32 v69, v163
	v_mov_b64_e32 v[58:59], v[26:27]
	s_or_saveexec_b64 s[2:3], s[2:3]
	v_readlane_b32 s34, v254, 2
	v_readlane_b32 s35, v254, 3
	s_nop 1
	v_mov_b64_e32 v[76:77], s[34:35]
	s_xor_b64 exec, exec, s[2:3]
	v_ashrrev_i32_e32 v27, 31, v26
	v_mov_b64_e32 v[76:77], s[0:1]
	v_mov_b64_e32 v[68:69], v[26:27]
	v_mov_b64_e32 v[58:59], v[26:27]
	s_or_b64 exec, exec, s[2:3]
	s_mov_b64 s[2:3], 0

; DI const float* xrow_ptr(const Params& p, int l, int row) {
;   if (l > 0) return p.out + (size_t)row * D;
;   return row < NP ? p.in[0] + (size_t)row * D : p.in[1] + (size_t)(row - NP) * D;
; }
; DI void phase7(const Params& p, int l, unsigned char* smem) {
;     ...
;     foreach_acc(acc, m0, n0, [&](int row, int col, float v) {
;       float xo = xrow_ptr(p, l, row)[col];
;       float gt = mod[(l * 10 + bidx_of(row)) * 3072 + 2048 + col];
;       p.out[(size_t)row * D + col] = xo + gt * v;
;     });
.LBB0_1365:
	v_subrev_u32_e32 v76, s0, v76
	v_and_or_b32 v76, v76, 40, v242
	ds_read_b64 v[76:77], v76
	v_lshlrev_b64 v[68:69], 12, v[68:69]
	v_cmp_gt_i32_e32 vcc, s50, v26
	v_lshlrev_b64 v[58:59], 12, v[58:59]
	v_lshl_add_u64 v[58:59], v[64:65], 0, v[58:59]
	v_cmp_lt_i32_e64 s[34:35], s64, v26
	s_mov_b64 s[2:3], -1
	s_waitcnt lgkmcnt(0)
	v_lshl_add_u64 v[68:69], v[76:77], 0, v[68:69]
	v_lshl_add_u64 v[68:69], v[162:163], 2, v[68:69]
	v_add_u32_e32 v76, 0xffffc000, v26
	global_load_dword v75, v[68:69], off
	v_lshrrev_b32_e32 v68, 4, v76
	v_add_u32_e32 v68, 2, v68
	v_cndmask_b32_e32 v68, v68, v121, vcc
	v_add_u32_e32 v68, s94, v68
	v_mul_lo_u32 v90, v68, s74
	v_add_u32_e32 v68, v90, v120
	v_ashrrev_i32_e32 v69, 31, v68
	v_lshl_add_u64 v[68:69], v[68:69], 2, s[78:79]
	global_load_dword v68, v[68:69], off
	s_and_b64 vcc, exec, s[6:7]
	s_waitcnt vmcnt(0)
	v_fmac_f32_e32 v75, v28, v68
	global_store_dword v[58:59], v75, off
	v_or_b32_e32 v58, v43, v136
	v_cmp_lt_i32_e64 s[36:37], s64, v58
	s_cbranch_vccnz .LBB0_1371
	s_and_saveexec_b64 s[2:3], s[36:37]
	s_xor_b64 s[2:3], exec, s[2:3]
	v_mov_b32_e32 v59, v163
	v_add_u32_e32 v78, 0xffffc000, v58
	v_mov_b32_e32 v79, v163
	v_mov_b64_e32 v[68:69], v[58:59]
	s_or_saveexec_b64 s[2:3], s[2:3]
	v_readlane_b32 s36, v254, 2
	v_readlane_b32 s37, v254, 3
	s_nop 1
	v_mov_b64_e32 v[80:81], s[36:37]
	s_xor_b64 exec, exec, s[2:3]
	v_ashrrev_i32_e32 v59, 31, v58
	v_mov_b64_e32 v[80:81], s[0:1]
	v_mov_b64_e32 v[78:79], v[58:59]
	v_mov_b64_e32 v[68:69], v[58:59]
	s_or_b64 exec, exec, s[2:3]
	s_mov_b64 s[2:3], 0

; DI const float* xrow_ptr(const Params& p, int l, int row) {
;   if (l > 0) return p.out + (size_t)row * D;
;   return row < NP ? p.in[0] + (size_t)row * D : p.in[1] + (size_t)(row - NP) * D;
; }
; DI void phase7(const Params& p, int l, unsigned char* smem) {
;     ...
;     foreach_acc(acc, m0, n0, [&](int row, int col, float v) {
;       float xo = xrow_ptr(p, l, row)[col];
;       float gt = mod[(l * 10 + bidx_of(row)) * 3072 + 2048 + col];
;       p.out[(size_t)row * D + col] = xo + gt * v;
;     });
.LBB0_1373:
	v_subrev_u32_e32 v80, s0, v80
	v_and_or_b32 v80, v80, 40, v242
	ds_read_b64 v[80:81], v80
	v_lshlrev_b64 v[78:79], 12, v[78:79]
	v_cmp_gt_i32_e32 vcc, s50, v58
	v_cmp_lt_i32_e64 s[36:37], s64, v58
	s_mov_b64 s[2:3], -1
	s_waitcnt lgkmcnt(0)
	v_lshl_add_u64 v[78:79], v[80:81], 0, v[78:79]
	v_lshl_add_u64 v[78:79], v[162:163], 2, v[78:79]
	global_load_dword v75, v[78:79], off
	v_add_u32_e32 v78, 0xffffc000, v58
	v_lshrrev_b32_e32 v28, 4, v78
	v_add_u32_e32 v28, 2, v28
	v_cndmask_b32_e32 v28, v28, v121, vcc
	v_add_u32_e32 v28, s94, v28
	v_mul_lo_u32 v91, v28, s74
	v_add_u32_e32 v80, v91, v120
	v_ashrrev_i32_e32 v81, 31, v80
	v_lshl_add_u64 v[80:81], v[80:81], 2, s[78:79]
	global_load_dword v28, v[80:81], off
	s_and_b64 vcc, exec, s[6:7]
	s_waitcnt vmcnt(0)
	v_fmac_f32_e32 v75, v29, v28
	v_lshlrev_b64 v[28:29], 12, v[68:69]
	v_lshl_add_u64 v[28:29], v[64:65], 0, v[28:29]
	global_store_dword v[28:29], v75, off
	v_or_b32_e32 v28, v43, v137
	v_cmp_lt_i32_e64 s[38:39], s64, v28
	s_cbranch_vccnz .LBB0_1379
	s_and_saveexec_b64 s[2:3], s[38:39]
	s_xor_b64 s[2:3], exec, s[2:3]
	v_mov_b32_e32 v29, v163
	v_add_u32_e32 v80, 0xffffc000, v28
	v_mov_b32_e32 v81, v163
	v_mov_b64_e32 v[68:69], v[28:29]
	s_or_saveexec_b64 s[2:3], s[2:3]
	v_readlane_b32 s38, v254, 2
	v_readlane_b32 s39, v254, 3
	s_nop 1
	v_mov_b64_e32 v[82:83], s[38:39]
	s_xor_b64 exec, exec, s[2:3]
	v_ashrrev_i32_e32 v29, 31, v28
	v_mov_b64_e32 v[82:83], s[0:1]
	v_mov_b64_e32 v[80:81], v[28:29]
	v_mov_b64_e32 v[68:69], v[28:29]
	s_or_b64 exec, exec, s[2:3]
	s_mov_b64 s[2:3], 0

; DI const float* xrow_ptr(const Params& p, int l, int row) {
;   if (l > 0) return p.out + (size_t)row * D;
;   return row < NP ? p.in[0] + (size_t)row * D : p.in[1] + (size_t)(row - NP) * D;
; }
; DI void phase7(const Params& p, int l, unsigned char* smem) {
;     ...
;     foreach_acc(acc, m0, n0, [&](int row, int col, float v) {
;       float xo = xrow_ptr(p, l, row)[col];
;       float gt = mod[(l * 10 + bidx_of(row)) * 3072 + 2048 + col];
;       p.out[(size_t)row * D + col] = xo + gt * v;
;     });
.LBB0_1381:
	v_subrev_u32_e32 v82, s0, v82
	v_and_or_b32 v82, v82, 40, v242
	ds_read_b64 v[82:83], v82
	v_lshlrev_b64 v[80:81], 12, v[80:81]
	v_cmp_gt_i32_e32 vcc, s50, v28
	v_lshlrev_b64 v[68:69], 12, v[68:69]
	v_lshl_add_u64 v[68:69], v[64:65], 0, v[68:69]
	v_cmp_lt_i32_e64 s[38:39], s64, v28
	s_mov_b64 s[2:3], -1
	s_waitcnt lgkmcnt(0)
	v_lshl_add_u64 v[80:81], v[82:83], 0, v[80:81]
	v_lshl_add_u64 v[80:81], v[162:163], 2, v[80:81]
	global_load_dword v75, v[80:81], off
	v_add_u32_e32 v80, 0xffffc000, v28
	v_lshrrev_b32_e32 v77, 4, v80
	v_add_u32_e32 v77, 2, v77
	v_cndmask_b32_e32 v77, v77, v121, vcc
	v_add_u32_e32 v77, s94, v77
	v_mul_lo_u32 v92, v77, s74
	v_add_u32_e32 v82, v92, v120
	v_ashrrev_i32_e32 v83, 31, v82
	v_lshl_add_u64 v[82:83], v[82:83], 2, s[78:79]
	global_load_dword v77, v[82:83], off
	s_and_b64 vcc, exec, s[6:7]
	s_waitcnt vmcnt(0)
	v_fmac_f32_e32 v75, v30, v77
	global_store_dword v[68:69], v75, off
	v_or_b32_e32 v68, v43, v138
	v_cmp_lt_i32_e64 s[40:41], s64, v68
	s_cbranch_vccnz .LBB0_1387
	s_and_saveexec_b64 s[2:3], s[40:41]
	s_xor_b64 s[2:3], exec, s[2:3]
	v_mov_b32_e32 v69, v163
	v_add_u32_e32 v84, 0xffffc000, v68
	v_mov_b32_e32 v85, v163
	v_mov_b64_e32 v[82:83], v[68:69]
	s_or_saveexec_b64 s[2:3], s[2:3]
	v_readlane_b32 s40, v254, 2
	v_readlane_b32 s41, v254, 3
	s_nop 1
	v_mov_b64_e32 v[86:87], s[40:41]
	s_xor_b64 exec, exec, s[2:3]
	v_ashrrev_i32_e32 v69, 31, v68
	v_mov_b64_e32 v[86:87], s[0:1]
	v_mov_b64_e32 v[84:85], v[68:69]
	v_mov_b64_e32 v[82:83], v[68:69]
	s_or_b64 exec, exec, s[2:3]
	s_mov_b64 s[2:3], 0

; DI const float* xrow_ptr(const Params& p, int l, int row) {
;   if (l > 0) return p.out + (size_t)row * D;
;   return row < NP ? p.in[0] + (size_t)row * D : p.in[1] + (size_t)(row - NP) * D;
; }
; DI void phase7(const Params& p, int l, unsigned char* smem) {
;     ...
;     foreach_acc(acc, m0, n0, [&](int row, int col, float v) {
;       float xo = xrow_ptr(p, l, row)[col];
;       float gt = mod[(l * 10 + bidx_of(row)) * 3072 + 2048 + col];
;       p.out[(size_t)row * D + col] = xo + gt * v;
;     });
.LBB0_1389:
	v_subrev_u32_e32 v86, s0, v86
	v_and_or_b32 v86, v86, 40, v242
	ds_read_b64 v[86:87], v86
	v_add_u32_e32 v30, 0xffffc000, v68
	v_lshrrev_b32_e32 v75, 4, v30
	v_cmp_gt_i32_e32 vcc, s50, v68
	v_add_u32_e32 v75, 2, v75
	v_lshlrev_b64 v[84:85], 12, v[84:85]
	v_cndmask_b32_e32 v75, v75, v121, vcc
	v_add_u32_e32 v75, s94, v75
	v_lshlrev_b64 v[82:83], 12, v[82:83]
	v_cmp_lt_i32_e64 s[40:41], s64, v68
	v_lshl_add_u64 v[82:83], v[64:65], 0, v[82:83]
	s_mov_b64 s[2:3], -1
	s_and_b64 vcc, exec, s[6:7]
	s_waitcnt lgkmcnt(0)
	v_lshl_add_u64 v[84:85], v[86:87], 0, v[84:85]
	v_lshl_add_u64 v[84:85], v[162:163], 2, v[84:85]
	v_mul_lo_u32 v86, v75, s74
	global_load_dword v43, v[84:85], off
	v_add_u32_e32 v84, v86, v120
	v_ashrrev_i32_e32 v85, 31, v84
	v_lshl_add_u64 v[84:85], v[84:85], 2, s[78:79]
	global_load_dword v75, v[84:85], off
	s_waitcnt vmcnt(0)
	v_fmac_f32_e32 v43, v31, v75
	global_store_dword v[82:83], v43, off
	s_cbranch_vccnz .LBB0_1395
	s_and_saveexec_b64 s[2:3], s[8:9]
	s_xor_b64 s[2:3], exec, s[2:3]
	v_mov_b32_e32 v43, v163
	v_mov_b32_e32 v82, v32
	v_mov_b32_e32 v83, v163
	s_or_saveexec_b64 s[2:3], s[2:3]
	v_readlane_b32 s8, v254, 2
	v_readlane_b32 s9, v254, 3
	s_nop 1
	v_mov_b64_e32 v[84:85], s[8:9]
	s_xor_b64 exec, exec, s[2:3]
	v_mov_b64_e32 v[84:85], s[0:1]
	v_mov_b64_e32 v[42:43], v[32:33]
	v_mov_b64_e32 v[82:83], v[32:33]
	s_or_b64 exec, exec, s[2:3]
	s_mov_b64 s[2:3], 0

; DI const float* xrow_ptr(const Params& p, int l, int row) {
;   if (l > 0) return p.out + (size_t)row * D;
;   return row < NP ? p.in[0] + (size_t)row * D : p.in[1] + (size_t)(row - NP) * D;
; }
; DI void phase7(const Params& p, int l, unsigned char* smem) {
;     ...
;     foreach_acc(acc, m0, n0, [&](int row, int col, float v) {
;       float xo = xrow_ptr(p, l, row)[col];
;       float gt = mod[(l * 10 + bidx_of(row)) * 3072 + 2048 + col];
;       p.out[(size_t)row * D + col] = xo + gt * v;
;     });
.LBB0_1397:
	v_subrev_u32_e32 v32, s0, v84
	v_and_or_b32 v32, v32, 40, v242
	ds_read_b64 v[32:33], v32
	v_lshlrev_b64 v[42:43], 12, v[42:43]
	s_mov_b64 s[2:3], -1
	s_and_b64 vcc, exec, s[6:7]
	s_waitcnt lgkmcnt(0)
	v_lshl_add_u64 v[32:33], v[32:33], 0, v[42:43]
	v_lshl_add_u64 v[32:33], v[162:163], 2, v[32:33]
	global_load_dword v31, v[32:33], off offset:128
	v_add_u32_e32 v32, v47, v118
	v_ashrrev_i32_e32 v33, 31, v32
	v_lshl_add_u64 v[32:33], v[32:33], 2, s[78:79]
	global_load_dword v32, v[32:33], off
	s_waitcnt vmcnt(0)
	v_fmac_f32_e32 v31, v0, v32
	v_lshlrev_b64 v[32:33], 12, v[82:83]
	v_lshl_add_u64 v[32:33], v[64:65], 0, v[32:33]
	global_store_dword v[32:33], v31, off offset:128
	s_cbranch_vccnz .LBB0_1403
	s_and_saveexec_b64 s[2:3], s[10:11]
	s_xor_b64 s[2:3], exec, s[2:3]
	v_mov_b32_e32 v47, v163
	v_mov_b32_e32 v32, v34
	v_mov_b32_e32 v33, v163
	s_or_saveexec_b64 s[2:3], s[2:3]
	v_readlane_b32 s8, v254, 2
	v_readlane_b32 s9, v254, 3
	s_nop 1
	v_mov_b64_e32 v[42:43], s[8:9]
	s_xor_b64 exec, exec, s[2:3]
	v_mov_b64_e32 v[42:43], s[0:1]
	v_mov_b64_e32 v[46:47], v[34:35]
	v_mov_b64_e32 v[32:33], v[34:35]
	s_or_b64 exec, exec, s[2:3]
	s_mov_b64 s[2:3], 0

; DI const float* xrow_ptr(const Params& p, int l, int row) {
;   if (l > 0) return p.out + (size_t)row * D;
;   return row < NP ? p.in[0] + (size_t)row * D : p.in[1] + (size_t)(row - NP) * D;
; }
; DI void phase7(const Params& p, int l, unsigned char* smem) {
;     ...
;     foreach_acc(acc, m0, n0, [&](int row, int col, float v) {
;       float xo = xrow_ptr(p, l, row)[col];
;       float gt = mod[(l * 10 + bidx_of(row)) * 3072 + 2048 + col];
;       p.out[(size_t)row * D + col] = xo + gt * v;
;     });
.LBB0_1405:
	v_subrev_u32_e32 v34, s0, v42
	v_and_or_b32 v34, v34, 40, v242
	ds_read_b64 v[34:35], v34
	v_lshlrev_b64 v[42:43], 12, v[46:47]
	s_mov_b64 s[2:3], -1
	s_and_b64 vcc, exec, s[6:7]
	s_waitcnt lgkmcnt(0)
	v_lshl_add_u64 v[34:35], v[34:35], 0, v[42:43]
	v_lshl_add_u64 v[34:35], v[162:163], 2, v[34:35]
	global_load_dword v31, v[34:35], off offset:128
	v_add_u32_e32 v34, v49, v118
	v_ashrrev_i32_e32 v35, 31, v34
	v_lshl_add_u64 v[34:35], v[34:35], 2, s[78:79]
	global_load_dword v0, v[34:35], off
	s_waitcnt vmcnt(0)
	v_fmac_f32_e32 v31, v1, v0
	v_lshlrev_b64 v[0:1], 12, v[32:33]
	v_lshl_add_u64 v[0:1], v[64:65], 0, v[0:1]
	global_store_dword v[0:1], v31, off offset:128
	s_cbranch_vccnz .LBB0_1411
	s_and_saveexec_b64 s[2:3], s[12:13]
	s_xor_b64 s[2:3], exec, s[2:3]
	v_mov_b32_e32 v49, v163
	v_mov_b32_e32 v0, v16
	v_mov_b32_e32 v1, v163
	s_or_saveexec_b64 s[2:3], s[2:3]
	v_readlane_b32 s8, v254, 2
	v_readlane_b32 s9, v254, 3
	s_nop 1
	v_mov_b64_e32 v[32:33], s[8:9]
	s_xor_b64 exec, exec, s[2:3]
	v_mov_b64_e32 v[32:33], s[0:1]
	v_mov_b64_e32 v[48:49], v[16:17]
	v_mov_b64_e32 v[0:1], v[16:17]
	s_or_b64 exec, exec, s[2:3]
	s_mov_b64 s[2:3], 0

; DI const float* xrow_ptr(const Params& p, int l, int row) {
;   if (l > 0) return p.out + (size_t)row * D;
;   return row < NP ? p.in[0] + (size_t)row * D : p.in[1] + (size_t)(row - NP) * D;
; }
; DI void phase7(const Params& p, int l, unsigned char* smem) {
;     ...
;     foreach_acc(acc, m0, n0, [&](int row, int col, float v) {
;       float xo = xrow_ptr(p, l, row)[col];
;       float gt = mod[(l * 10 + bidx_of(row)) * 3072 + 2048 + col];
;       p.out[(size_t)row * D + col] = xo + gt * v;
;     });
.LBB0_1413:
	v_subrev_u32_e32 v16, s0, v32
	v_and_or_b32 v16, v16, 40, v242
	ds_read_b64 v[16:17], v16
	v_lshlrev_b64 v[32:33], 12, v[48:49]
	v_lshlrev_b64 v[0:1], 12, v[0:1]
	v_lshl_add_u64 v[0:1], v[64:65], 0, v[0:1]
	s_mov_b64 s[2:3], -1
	s_and_b64 vcc, exec, s[6:7]
	s_waitcnt lgkmcnt(0)
	v_lshl_add_u64 v[16:17], v[16:17], 0, v[32:33]
	v_lshl_add_u64 v[16:17], v[162:163], 2, v[16:17]
	global_load_dword v31, v[16:17], off offset:128
	v_add_u32_e32 v16, v53, v118
	v_ashrrev_i32_e32 v17, 31, v16
	v_lshl_add_u64 v[16:17], v[16:17], 2, s[78:79]
	global_load_dword v16, v[16:17], off
	s_waitcnt vmcnt(0)
	v_fmac_f32_e32 v31, v2, v16
	global_store_dword v[0:1], v31, off offset:128
	s_cbranch_vccnz .LBB0_1419
	s_and_saveexec_b64 s[2:3], s[14:15]
	s_xor_b64 s[2:3], exec, s[2:3]
	v_mov_b32_e32 v53, v163
	v_mov_b32_e32 v0, v36
	v_mov_b32_e32 v1, v163
	s_or_saveexec_b64 s[2:3], s[2:3]
	v_readlane_b32 s8, v254, 2
	v_readlane_b32 s9, v254, 3
	s_nop 1
	v_mov_b64_e32 v[16:17], s[8:9]
	s_xor_b64 exec, exec, s[2:3]
	v_mov_b64_e32 v[16:17], s[0:1]
	v_mov_b64_e32 v[52:53], v[36:37]
	v_mov_b64_e32 v[0:1], v[36:37]
	s_or_b64 exec, exec, s[2:3]
	s_mov_b64 s[2:3], 0

; DI const float* xrow_ptr(const Params& p, int l, int row) {
;   if (l > 0) return p.out + (size_t)row * D;
;   return row < NP ? p.in[0] + (size_t)row * D : p.in[1] + (size_t)(row - NP) * D;
; }
; DI void phase7(const Params& p, int l, unsigned char* smem) {
;     ...
;     foreach_acc(acc, m0, n0, [&](int row, int col, float v) {
;       float xo = xrow_ptr(p, l, row)[col];
;       float gt = mod[(l * 10 + bidx_of(row)) * 3072 + 2048 + col];
;       p.out[(size_t)row * D + col] = xo + gt * v;
;     });
.LBB0_1421:
	v_subrev_u32_e32 v16, s0, v16
	v_and_or_b32 v16, v16, 40, v242
	ds_read_b64 v[16:17], v16
	v_lshlrev_b64 v[32:33], 12, v[52:53]
	v_lshlrev_b64 v[0:1], 12, v[0:1]
	v_lshl_add_u64 v[0:1], v[64:65], 0, v[0:1]
	s_mov_b64 s[2:3], -1
	s_and_b64 vcc, exec, s[6:7]
	s_waitcnt lgkmcnt(0)
	v_lshl_add_u64 v[16:17], v[16:17], 0, v[32:33]
	v_lshl_add_u64 v[16:17], v[162:163], 2, v[16:17]
	global_load_dword v2, v[16:17], off offset:128
	v_add_u32_e32 v16, v55, v118
	v_ashrrev_i32_e32 v17, 31, v16
	v_lshl_add_u64 v[16:17], v[16:17], 2, s[78:79]
	global_load_dword v16, v[16:17], off
	s_waitcnt vmcnt(0)
	v_fmac_f32_e32 v2, v3, v16
	global_store_dword v[0:1], v2, off offset:128
	s_cbranch_vccnz .LBB0_1427
	s_and_saveexec_b64 s[2:3], s[16:17]
	s_xor_b64 s[2:3], exec, s[2:3]
	v_mov_b32_e32 v55, v163
	v_mov_b32_e32 v0, v18
	v_mov_b32_e32 v1, v163
	s_or_saveexec_b64 s[2:3], s[2:3]
	v_readlane_b32 s8, v254, 2
	v_readlane_b32 s9, v254, 3
	s_nop 1
	v_mov_b64_e32 v[2:3], s[8:9]
	s_xor_b64 exec, exec, s[2:3]
	v_mov_b64_e32 v[2:3], s[0:1]
	v_mov_b64_e32 v[54:55], v[18:19]
	v_mov_b64_e32 v[0:1], v[18:19]
	s_or_b64 exec, exec, s[2:3]
	s_mov_b64 s[2:3], 0

; DI const float* xrow_ptr(const Params& p, int l, int row) {
;   if (l > 0) return p.out + (size_t)row * D;
;   return row < NP ? p.in[0] + (size_t)row * D : p.in[1] + (size_t)(row - NP) * D;
; }
; DI void phase7(const Params& p, int l, unsigned char* smem) {
;     ...
;     foreach_acc(acc, m0, n0, [&](int row, int col, float v) {
;       float xo = xrow_ptr(p, l, row)[col];
;       float gt = mod[(l * 10 + bidx_of(row)) * 3072 + 2048 + col];
;       p.out[(size_t)row * D + col] = xo + gt * v;
;     });
.LBB0_1429:
	v_subrev_u32_e32 v2, s0, v2
	v_and_or_b32 v2, v2, 40, v242
	ds_read_b64 v[2:3], v2
	v_lshlrev_b64 v[16:17], 12, v[54:55]
	v_lshlrev_b64 v[0:1], 12, v[0:1]
	v_lshl_add_u64 v[0:1], v[64:65], 0, v[0:1]
	s_mov_b64 s[2:3], -1
	s_and_b64 vcc, exec, s[6:7]
	s_mov_b32 s16, s46
	v_readlane_b32 s17, v254, 59
	s_waitcnt lgkmcnt(0)
	v_lshl_add_u64 v[2:3], v[2:3], 0, v[16:17]
	v_lshl_add_u64 v[2:3], v[162:163], 2, v[2:3]
	global_load_dword v16, v[2:3], off offset:128
	v_add_u32_e32 v2, v57, v118
	v_ashrrev_i32_e32 v3, 31, v2
	v_lshl_add_u64 v[2:3], v[2:3], 2, s[78:79]
	global_load_dword v2, v[2:3], off
	s_waitcnt vmcnt(0)
	v_fmac_f32_e32 v16, v4, v2
	global_store_dword v[0:1], v16, off offset:128
	s_cbranch_vccnz .LBB0_1435
	s_and_saveexec_b64 s[2:3], s[18:19]
	s_xor_b64 s[2:3], exec, s[2:3]
	v_mov_b32_e32 v57, v163
	v_mov_b32_e32 v0, v38
	v_mov_b32_e32 v1, v163
	s_or_saveexec_b64 s[2:3], s[2:3]
	v_readlane_b32 s8, v254, 2
	v_readlane_b32 s9, v254, 3
	s_nop 1
	v_mov_b64_e32 v[2:3], s[8:9]
	s_xor_b64 exec, exec, s[2:3]
	v_mov_b64_e32 v[2:3], s[0:1]
	v_mov_b64_e32 v[56:57], v[38:39]
	v_mov_b64_e32 v[0:1], v[38:39]
	s_or_b64 exec, exec, s[2:3]
	s_mov_b64 s[2:3], 0

; DI const float* xrow_ptr(const Params& p, int l, int row) {
;   if (l > 0) return p.out + (size_t)row * D;
;   return row < NP ? p.in[0] + (size_t)row * D : p.in[1] + (size_t)(row - NP) * D;
; }
; DI void phase7(const Params& p, int l, unsigned char* smem) {
;     ...
;     foreach_acc(acc, m0, n0, [&](int row, int col, float v) {
;       float xo = xrow_ptr(p, l, row)[col];
;       float gt = mod[(l * 10 + bidx_of(row)) * 3072 + 2048 + col];
;       p.out[(size_t)row * D + col] = xo + gt * v;
;     });
.LBB0_1437:
	v_subrev_u32_e32 v2, s0, v2
	v_and_or_b32 v2, v2, 40, v242
	ds_read_b64 v[2:3], v2
	v_lshlrev_b64 v[16:17], 12, v[56:57]
	v_lshlrev_b64 v[0:1], 12, v[0:1]
	v_lshl_add_u64 v[0:1], v[64:65], 0, v[0:1]
	s_mov_b64 s[2:3], -1
	s_and_b64 vcc, exec, s[6:7]
	s_waitcnt lgkmcnt(0)
	v_lshl_add_u64 v[2:3], v[2:3], 0, v[16:17]
	v_lshl_add_u64 v[2:3], v[162:163], 2, v[2:3]
	global_load_dword v4, v[2:3], off offset:128
	v_add_u32_e32 v2, v61, v118
	v_ashrrev_i32_e32 v3, 31, v2
	v_lshl_add_u64 v[2:3], v[2:3], 2, s[78:79]
	global_load_dword v2, v[2:3], off
	s_waitcnt vmcnt(0)
	v_fmac_f32_e32 v4, v5, v2
	global_store_dword v[0:1], v4, off offset:128
	s_cbranch_vccnz .LBB0_1443
	s_and_saveexec_b64 s[2:3], s[20:21]
	s_xor_b64 s[2:3], exec, s[2:3]
	v_mov_b32_e32 v61, v163
	v_mov_b32_e32 v0, v20
	v_mov_b32_e32 v1, v163
	s_or_saveexec_b64 s[2:3], s[2:3]
	v_readlane_b32 s8, v254, 2
	v_readlane_b32 s9, v254, 3
	s_nop 1
	v_mov_b64_e32 v[2:3], s[8:9]
	s_xor_b64 exec, exec, s[2:3]
	v_mov_b64_e32 v[2:3], s[0:1]
	v_mov_b64_e32 v[60:61], v[20:21]
	v_mov_b64_e32 v[0:1], v[20:21]
	s_or_b64 exec, exec, s[2:3]
	s_mov_b64 s[2:3], 0

; DI const float* xrow_ptr(const Params& p, int l, int row) {
;   if (l > 0) return p.out + (size_t)row * D;
;   return row < NP ? p.in[0] + (size_t)row * D : p.in[1] + (size_t)(row - NP) * D;
; }
; DI void phase7(const Params& p, int l, unsigned char* smem) {
;     ...
;     foreach_acc(acc, m0, n0, [&](int row, int col, float v) {
;       float xo = xrow_ptr(p, l, row)[col];
;       float gt = mod[(l * 10 + bidx_of(row)) * 3072 + 2048 + col];
;       p.out[(size_t)row * D + col] = xo + gt * v;
;     });
.LBB0_1445:
	v_subrev_u32_e32 v2, s0, v2
	v_and_or_b32 v2, v2, 40, v242
	ds_read_b64 v[2:3], v2
	v_lshlrev_b64 v[4:5], 12, v[60:61]
	v_lshlrev_b64 v[0:1], 12, v[0:1]
	v_readlane_b32 s20, v254, 61
	v_lshl_add_u64 v[0:1], v[64:65], 0, v[0:1]
	s_mov_b64 s[2:3], -1
	s_and_b64 vcc, exec, s[6:7]
	v_readlane_b32 s21, v254, 62
	s_waitcnt lgkmcnt(0)
	v_lshl_add_u64 v[2:3], v[2:3], 0, v[4:5]
	v_lshl_add_u64 v[2:3], v[162:163], 2, v[2:3]
	global_load_dword v4, v[2:3], off offset:128
	v_add_u32_e32 v2, v63, v118
	v_ashrrev_i32_e32 v3, 31, v2
	v_lshl_add_u64 v[2:3], v[2:3], 2, s[78:79]
	global_load_dword v2, v[2:3], off
	s_waitcnt vmcnt(0)
	v_fmac_f32_e32 v4, v6, v2
	global_store_dword v[0:1], v4, off offset:128
	s_cbranch_vccnz .LBB0_1451
	s_and_saveexec_b64 s[2:3], s[22:23]
	s_xor_b64 s[2:3], exec, s[2:3]
	v_mov_b32_e32 v63, v163
	v_mov_b32_e32 v0, v40
	v_mov_b32_e32 v1, v163
	s_or_saveexec_b64 s[2:3], s[2:3]
	v_readlane_b32 s8, v254, 2
	v_readlane_b32 s9, v254, 3
	s_nop 1
	v_mov_b64_e32 v[2:3], s[8:9]
	s_xor_b64 exec, exec, s[2:3]
	v_mov_b64_e32 v[2:3], s[0:1]
	v_mov_b64_e32 v[62:63], v[40:41]
	v_mov_b64_e32 v[0:1], v[40:41]
	s_or_b64 exec, exec, s[2:3]
	s_mov_b64 s[2:3], 0

; DI const float* xrow_ptr(const Params& p, int l, int row) {
;   if (l > 0) return p.out + (size_t)row * D;
;   return row < NP ? p.in[0] + (size_t)row * D : p.in[1] + (size_t)(row - NP) * D;
; }
; DI void phase7(const Params& p, int l, unsigned char* smem) {
;     ...
;     foreach_acc(acc, m0, n0, [&](int row, int col, float v) {
;       float xo = xrow_ptr(p, l, row)[col];
;       float gt = mod[(l * 10 + bidx_of(row)) * 3072 + 2048 + col];
;       p.out[(size_t)row * D + col] = xo + gt * v;
;     });
.LBB0_1453:
	v_subrev_u32_e32 v2, s0, v2
	v_and_or_b32 v2, v2, 40, v242
	ds_read_b64 v[2:3], v2
	v_lshlrev_b64 v[4:5], 12, v[62:63]
	v_lshlrev_b64 v[0:1], 12, v[0:1]
	v_lshl_add_u64 v[0:1], v[64:65], 0, v[0:1]
	s_mov_b64 s[2:3], -1
	s_and_b64 vcc, exec, s[6:7]
	s_waitcnt lgkmcnt(0)
	v_lshl_add_u64 v[2:3], v[2:3], 0, v[4:5]
	v_lshl_add_u64 v[2:3], v[162:163], 2, v[2:3]
	global_load_dword v4, v[2:3], off offset:128
	v_add_u32_e32 v2, v67, v118
	v_ashrrev_i32_e32 v3, 31, v2
	v_lshl_add_u64 v[2:3], v[2:3], 2, s[78:79]
	global_load_dword v2, v[2:3], off
	s_waitcnt vmcnt(0)
	v_fmac_f32_e32 v4, v7, v2
	global_store_dword v[0:1], v4, off offset:128
	s_cbranch_vccnz .LBB0_1459
	s_and_saveexec_b64 s[2:3], s[24:25]
	s_xor_b64 s[2:3], exec, s[2:3]
	v_mov_b32_e32 v67, v163
	v_mov_b32_e32 v0, v22
	v_mov_b32_e32 v1, v163
	s_or_saveexec_b64 s[2:3], s[2:3]
	v_readlane_b32 s8, v254, 2
	v_readlane_b32 s9, v254, 3
	s_nop 1
	v_mov_b64_e32 v[2:3], s[8:9]
	s_xor_b64 exec, exec, s[2:3]
	v_mov_b64_e32 v[2:3], s[0:1]
	v_mov_b64_e32 v[66:67], v[22:23]
	v_mov_b64_e32 v[0:1], v[22:23]
	s_or_b64 exec, exec, s[2:3]
	s_mov_b64 s[2:3], 0

; DI const float* xrow_ptr(const Params& p, int l, int row) {
;   if (l > 0) return p.out + (size_t)row * D;
;   return row < NP ? p.in[0] + (size_t)row * D : p.in[1] + (size_t)(row - NP) * D;
; }
; DI void phase7(const Params& p, int l, unsigned char* smem) {
;     ...
;     foreach_acc(acc, m0, n0, [&](int row, int col, float v) {
;       float xo = xrow_ptr(p, l, row)[col];
;       float gt = mod[(l * 10 + bidx_of(row)) * 3072 + 2048 + col];
;       p.out[(size_t)row * D + col] = xo + gt * v;
;     });
.LBB0_1461:
	v_subrev_u32_e32 v2, s0, v2
	v_and_or_b32 v2, v2, 40, v242
	ds_read_b64 v[2:3], v2
	v_lshlrev_b64 v[4:5], 12, v[66:67]
	v_lshlrev_b64 v[0:1], 12, v[0:1]
	v_lshl_add_u64 v[0:1], v[64:65], 0, v[0:1]
	s_mov_b64 s[2:3], -1
	s_and_b64 vcc, exec, s[6:7]
	s_waitcnt lgkmcnt(0)
	v_lshl_add_u64 v[2:3], v[2:3], 0, v[4:5]
	v_lshl_add_u64 v[2:3], v[162:163], 2, v[2:3]
	global_load_dword v4, v[2:3], off offset:128
	v_add_u32_e32 v2, v71, v118
	v_ashrrev_i32_e32 v3, 31, v2
	v_lshl_add_u64 v[2:3], v[2:3], 2, s[78:79]
	global_load_dword v2, v[2:3], off
	s_waitcnt vmcnt(0)
	v_fmac_f32_e32 v4, v8, v2
	global_store_dword v[0:1], v4, off offset:128
	s_cbranch_vccnz .LBB0_1467
	s_and_saveexec_b64 s[2:3], s[26:27]
	s_xor_b64 s[2:3], exec, s[2:3]
	v_mov_b32_e32 v71, v163
	v_mov_b32_e32 v0, v44
	v_mov_b32_e32 v1, v163
	s_or_saveexec_b64 s[2:3], s[2:3]
	v_readlane_b32 s8, v254, 2
	v_readlane_b32 s9, v254, 3
	s_nop 1
	v_mov_b64_e32 v[2:3], s[8:9]
	s_xor_b64 exec, exec, s[2:3]
	v_mov_b64_e32 v[2:3], s[0:1]
	v_mov_b64_e32 v[70:71], v[44:45]
	v_mov_b64_e32 v[0:1], v[44:45]
	s_or_b64 exec, exec, s[2:3]
	s_mov_b64 s[2:3], 0

; DI const float* xrow_ptr(const Params& p, int l, int row) {
;   if (l > 0) return p.out + (size_t)row * D;
;   return row < NP ? p.in[0] + (size_t)row * D : p.in[1] + (size_t)(row - NP) * D;
; }
; DI void phase7(const Params& p, int l, unsigned char* smem) {
;     ...
;     foreach_acc(acc, m0, n0, [&](int row, int col, float v) {
;       float xo = xrow_ptr(p, l, row)[col];
;       float gt = mod[(l * 10 + bidx_of(row)) * 3072 + 2048 + col];
;       p.out[(size_t)row * D + col] = xo + gt * v;
;     });
.LBB0_1469:
	v_subrev_u32_e32 v2, s0, v2
	v_and_or_b32 v2, v2, 40, v242
	ds_read_b64 v[2:3], v2
	v_lshlrev_b64 v[4:5], 12, v[70:71]
	v_lshlrev_b64 v[0:1], 12, v[0:1]
	v_lshl_add_u64 v[0:1], v[64:65], 0, v[0:1]
	s_mov_b64 s[2:3], -1
	s_and_b64 vcc, exec, s[6:7]
	s_waitcnt lgkmcnt(0)
	v_lshl_add_u64 v[2:3], v[2:3], 0, v[4:5]
	v_lshl_add_u64 v[2:3], v[162:163], 2, v[2:3]
	global_load_dword v4, v[2:3], off offset:128
	v_add_u32_e32 v2, v73, v118
	v_ashrrev_i32_e32 v3, 31, v2
	v_lshl_add_u64 v[2:3], v[2:3], 2, s[78:79]
	global_load_dword v2, v[2:3], off
	s_waitcnt vmcnt(0)
	v_fmac_f32_e32 v4, v9, v2
	global_store_dword v[0:1], v4, off offset:128
	s_cbranch_vccnz .LBB0_1475
	s_and_saveexec_b64 s[2:3], s[28:29]
	s_xor_b64 s[2:3], exec, s[2:3]
	v_mov_b32_e32 v73, v163
	v_mov_b32_e32 v0, v24
	v_mov_b32_e32 v1, v163
	s_or_saveexec_b64 s[2:3], s[2:3]
	v_readlane_b32 s8, v254, 2
	v_readlane_b32 s9, v254, 3
	s_nop 1
	v_mov_b64_e32 v[2:3], s[8:9]
	s_xor_b64 exec, exec, s[2:3]
	v_mov_b64_e32 v[2:3], s[0:1]
	v_mov_b64_e32 v[72:73], v[24:25]
	v_mov_b64_e32 v[0:1], v[24:25]
	s_or_b64 exec, exec, s[2:3]
	s_mov_b64 s[2:3], 0

; DI const float* xrow_ptr(const Params& p, int l, int row) {
;   if (l > 0) return p.out + (size_t)row * D;
;   return row < NP ? p.in[0] + (size_t)row * D : p.in[1] + (size_t)(row - NP) * D;
; }
; DI void phase7(const Params& p, int l, unsigned char* smem) {
;     ...
;     foreach_acc(acc, m0, n0, [&](int row, int col, float v) {
;       float xo = xrow_ptr(p, l, row)[col];
;       float gt = mod[(l * 10 + bidx_of(row)) * 3072 + 2048 + col];
;       p.out[(size_t)row * D + col] = xo + gt * v;
;     });
.LBB0_1477:
	v_subrev_u32_e32 v2, s0, v2
	v_and_or_b32 v2, v2, 40, v242
	ds_read_b64 v[2:3], v2
	v_lshlrev_b64 v[4:5], 12, v[72:73]
	v_lshlrev_b64 v[0:1], 12, v[0:1]
	v_lshl_add_u64 v[0:1], v[64:65], 0, v[0:1]
	s_mov_b64 s[2:3], -1
	s_and_b64 vcc, exec, s[6:7]
	s_mov_b32 s29, 0x2aaaaaab
	s_waitcnt lgkmcnt(0)
	v_lshl_add_u64 v[2:3], v[2:3], 0, v[4:5]
	v_lshl_add_u64 v[2:3], v[162:163], 2, v[2:3]
	global_load_dword v4, v[2:3], off offset:128
	v_add_u32_e32 v2, v88, v118
	v_ashrrev_i32_e32 v3, 31, v2
	v_lshl_add_u64 v[2:3], v[2:3], 2, s[78:79]
	global_load_dword v2, v[2:3], off
	s_waitcnt vmcnt(0)
	v_fmac_f32_e32 v4, v10, v2
	global_store_dword v[0:1], v4, off offset:128
	s_cbranch_vccnz .LBB0_1483
	s_and_saveexec_b64 s[2:3], s[30:31]
	s_xor_b64 s[2:3], exec, s[2:3]
	v_mov_b32_e32 v75, v163
	v_mov_b32_e32 v0, v50
	v_mov_b32_e32 v1, v163
	s_or_saveexec_b64 s[2:3], s[2:3]
	v_readlane_b32 s8, v254, 2
	v_readlane_b32 s9, v254, 3
	s_nop 1
	v_mov_b64_e32 v[2:3], s[8:9]
	s_xor_b64 exec, exec, s[2:3]
	v_mov_b64_e32 v[2:3], s[0:1]
	v_mov_b64_e32 v[74:75], v[50:51]
	v_mov_b64_e32 v[0:1], v[50:51]
	s_or_b64 exec, exec, s[2:3]
	s_mov_b64 s[2:3], 0

; DI const float* xrow_ptr(const Params& p, int l, int row) {
;   if (l > 0) return p.out + (size_t)row * D;
;   return row < NP ? p.in[0] + (size_t)row * D : p.in[1] + (size_t)(row - NP) * D;
; }
; DI void phase7(const Params& p, int l, unsigned char* smem) {
;     ...
;     foreach_acc(acc, m0, n0, [&](int row, int col, float v) {
;       float xo = xrow_ptr(p, l, row)[col];
;       float gt = mod[(l * 10 + bidx_of(row)) * 3072 + 2048 + col];
;       p.out[(size_t)row * D + col] = xo + gt * v;
;     });
.LBB0_1485:
	v_subrev_u32_e32 v2, s0, v2
	v_and_or_b32 v2, v2, 40, v242
	ds_read_b64 v[2:3], v2
	v_lshlrev_b64 v[4:5], 12, v[74:75]
	v_lshlrev_b64 v[0:1], 12, v[0:1]
	v_lshl_add_u64 v[0:1], v[64:65], 0, v[0:1]
	s_mov_b64 s[2:3], -1
	s_and_b64 vcc, exec, s[6:7]
	s_waitcnt lgkmcnt(0)
	v_lshl_add_u64 v[2:3], v[2:3], 0, v[4:5]
	v_lshl_add_u64 v[2:3], v[162:163], 2, v[2:3]
	global_load_dword v4, v[2:3], off offset:128
	v_add_u32_e32 v2, v89, v118
	v_ashrrev_i32_e32 v3, 31, v2
	v_lshl_add_u64 v[2:3], v[2:3], 2, s[78:79]
	global_load_dword v2, v[2:3], off
	s_waitcnt vmcnt(0)
	v_fmac_f32_e32 v4, v11, v2
	global_store_dword v[0:1], v4, off offset:128
	s_cbranch_vccnz .LBB0_1491
	s_and_saveexec_b64 s[2:3], s[34:35]
	s_xor_b64 s[2:3], exec, s[2:3]
	v_mov_b32_e32 v77, v163
	v_mov_b32_e32 v0, v26
	v_mov_b32_e32 v1, v163
	s_or_saveexec_b64 s[2:3], s[2:3]
	v_readlane_b32 s8, v254, 2
	v_readlane_b32 s9, v254, 3
	s_nop 1
	v_mov_b64_e32 v[2:3], s[8:9]
	s_xor_b64 exec, exec, s[2:3]
	v_mov_b64_e32 v[2:3], s[0:1]
	v_mov_b64_e32 v[76:77], v[26:27]
	v_mov_b64_e32 v[0:1], v[26:27]
	s_or_b64 exec, exec, s[2:3]
	s_mov_b64 s[2:3], 0

; DI const float* xrow_ptr(const Params& p, int l, int row) {
;   if (l > 0) return p.out + (size_t)row * D;
;   return row < NP ? p.in[0] + (size_t)row * D : p.in[1] + (size_t)(row - NP) * D;
; }
; DI void phase7(const Params& p, int l, unsigned char* smem) {
;     ...
;     foreach_acc(acc, m0, n0, [&](int row, int col, float v) {
;       float xo = xrow_ptr(p, l, row)[col];
;       float gt = mod[(l * 10 + bidx_of(row)) * 3072 + 2048 + col];
;       p.out[(size_t)row * D + col] = xo + gt * v;
;     });
.LBB0_1493:
	v_subrev_u32_e32 v2, s0, v2
	v_and_or_b32 v2, v2, 40, v242
	ds_read_b64 v[2:3], v2
	v_lshlrev_b64 v[4:5], 12, v[76:77]
	v_lshlrev_b64 v[0:1], 12, v[0:1]
	v_lshl_add_u64 v[0:1], v[64:65], 0, v[0:1]
	s_mov_b64 s[2:3], -1
	s_and_b64 vcc, exec, s[6:7]
	s_waitcnt lgkmcnt(0)
	v_lshl_add_u64 v[2:3], v[2:3], 0, v[4:5]
	v_lshl_add_u64 v[2:3], v[162:163], 2, v[2:3]
	global_load_dword v4, v[2:3], off offset:128
	v_add_u32_e32 v2, v90, v118
	v_ashrrev_i32_e32 v3, 31, v2
	v_lshl_add_u64 v[2:3], v[2:3], 2, s[78:79]
	global_load_dword v2, v[2:3], off
	s_waitcnt vmcnt(0)
	v_fmac_f32_e32 v4, v12, v2
	global_store_dword v[0:1], v4, off offset:128
	s_cbranch_vccnz .LBB0_1499
	s_and_saveexec_b64 s[2:3], s[36:37]
	s_xor_b64 s[2:3], exec, s[2:3]
	v_mov_b32_e32 v79, v163
	v_mov_b32_e32 v0, v58
	v_mov_b32_e32 v1, v163
	s_or_saveexec_b64 s[2:3], s[2:3]
	v_readlane_b32 s8, v254, 2
	v_readlane_b32 s9, v254, 3
	s_nop 1
	v_mov_b64_e32 v[2:3], s[8:9]
	s_xor_b64 exec, exec, s[2:3]
	v_mov_b64_e32 v[2:3], s[0:1]
	v_mov_b64_e32 v[78:79], v[58:59]
	v_mov_b64_e32 v[0:1], v[58:59]
	s_or_b64 exec, exec, s[2:3]
	s_mov_b64 s[2:3], 0

; DI const float* xrow_ptr(const Params& p, int l, int row) {
;   if (l > 0) return p.out + (size_t)row * D;
;   return row < NP ? p.in[0] + (size_t)row * D : p.in[1] + (size_t)(row - NP) * D;
; }
; DI void phase7(const Params& p, int l, unsigned char* smem) {
;     ...
;     foreach_acc(acc, m0, n0, [&](int row, int col, float v) {
;       float xo = xrow_ptr(p, l, row)[col];
;       float gt = mod[(l * 10 + bidx_of(row)) * 3072 + 2048 + col];
;       p.out[(size_t)row * D + col] = xo + gt * v;
;     });
.LBB0_1501:
	v_subrev_u32_e32 v2, s0, v2
	v_and_or_b32 v2, v2, 40, v242
	ds_read_b64 v[2:3], v2
	v_lshlrev_b64 v[4:5], 12, v[78:79]
	v_lshlrev_b64 v[0:1], 12, v[0:1]
	v_lshl_add_u64 v[0:1], v[64:65], 0, v[0:1]
	s_mov_b64 s[2:3], -1
	s_and_b64 vcc, exec, s[6:7]
	v_readlane_b32 s25, v254, 31
	v_readlane_b32 s26, v254, 32
	s_movk_i32 s27, 0x200
	s_movk_i32 s28, 0x300
	s_mov_b64 s[30:31], 0x2000
	s_movk_i32 s34, 0xffa0
	s_waitcnt lgkmcnt(0)
	v_lshl_add_u64 v[2:3], v[2:3], 0, v[4:5]
	v_lshl_add_u64 v[2:3], v[162:163], 2, v[2:3]
	global_load_dword v4, v[2:3], off offset:128
	v_add_u32_e32 v2, v91, v118
	v_ashrrev_i32_e32 v3, 31, v2
	v_lshl_add_u64 v[2:3], v[2:3], 2, s[78:79]
	global_load_dword v2, v[2:3], off
	s_waitcnt vmcnt(0)
	v_fmac_f32_e32 v4, v13, v2
	global_store_dword v[0:1], v4, off offset:128
	s_cbranch_vccnz .LBB0_1507
	s_and_saveexec_b64 s[2:3], s[38:39]
	s_xor_b64 s[2:3], exec, s[2:3]
	v_mov_b32_e32 v81, v163
	v_mov_b32_e32 v0, v28
	v_mov_b32_e32 v1, v163
	s_or_saveexec_b64 s[2:3], s[2:3]
	v_readlane_b32 s8, v254, 2
	v_readlane_b32 s9, v254, 3
	s_nop 1
	v_mov_b64_e32 v[2:3], s[8:9]
	s_xor_b64 exec, exec, s[2:3]
	v_mov_b64_e32 v[2:3], s[0:1]
	v_mov_b64_e32 v[80:81], v[28:29]
	v_mov_b64_e32 v[0:1], v[28:29]
	s_or_b64 exec, exec, s[2:3]
	s_mov_b64 s[2:3], 0

; DI const float* xrow_ptr(const Params& p, int l, int row) {
;   if (l > 0) return p.out + (size_t)row * D;
;   return row < NP ? p.in[0] + (size_t)row * D : p.in[1] + (size_t)(row - NP) * D;
; }
; DI void phase7(const Params& p, int l, unsigned char* smem) {
;     ...
;     foreach_acc(acc, m0, n0, [&](int row, int col, float v) {
;       float xo = xrow_ptr(p, l, row)[col];
;       float gt = mod[(l * 10 + bidx_of(row)) * 3072 + 2048 + col];
;       p.out[(size_t)row * D + col] = xo + gt * v;
;     });
.LBB0_1509:
	v_subrev_u32_e32 v2, s0, v2
	v_and_or_b32 v2, v2, 40, v242
	ds_read_b64 v[2:3], v2
	v_lshlrev_b64 v[4:5], 12, v[80:81]
	v_add_u32_e32 v6, v92, v118
	v_ashrrev_i32_e32 v7, 31, v6
	v_lshl_add_u64 v[6:7], v[6:7], 2, s[78:79]
	global_load_dword v6, v[6:7], off
	v_lshlrev_b64 v[0:1], 12, v[0:1]
	s_and_b64 vcc, exec, s[6:7]
	v_lshl_add_u64 v[0:1], v[64:65], 0, v[0:1]
	s_mov_b64 s[2:3], -1
	s_waitcnt lgkmcnt(0)
	v_lshl_add_u64 v[2:3], v[2:3], 0, v[4:5]
	v_lshl_add_u64 v[2:3], v[162:163], 2, v[2:3]
	global_load_dword v2, v[2:3], off offset:128
	s_waitcnt vmcnt(0)
	v_fmac_f32_e32 v2, v14, v6
	global_store_dword v[0:1], v2, off offset:128
	s_cbranch_vccnz .LBB0_1515
	s_and_saveexec_b64 s[2:3], s[40:41]
	s_xor_b64 s[2:3], exec, s[2:3]
	v_mov_b32_e32 v31, v163
	v_mov_b32_e32 v0, v68
	v_mov_b32_e32 v1, v163
	s_or_saveexec_b64 s[2:3], s[2:3]
	v_readlane_b32 s6, v254, 2
	v_readlane_b32 s7, v254, 3
	s_nop 1
	v_mov_b64_e32 v[2:3], s[6:7]
	s_xor_b64 exec, exec, s[2:3]
	v_mov_b64_e32 v[2:3], s[0:1]
	v_mov_b64_e32 v[30:31], v[68:69]
	v_mov_b64_e32 v[0:1], v[68:69]
	s_or_b64 exec, exec, s[2:3]
	s_mov_b64 s[2:3], 0

; DI const float* xrow_ptr(const Params& p, int l, int row) {
;   if (l > 0) return p.out + (size_t)row * D;
;   return row < NP ? p.in[0] + (size_t)row * D : p.in[1] + (size_t)(row - NP) * D;
; }
; DI void phase7(const Params& p, int l, unsigned char* smem) {
;     ...
;     foreach_acc(acc, m0, n0, [&](int row, int col, float v) {
;       float xo = xrow_ptr(p, l, row)[col];
;       float gt = mod[(l * 10 + bidx_of(row)) * 3072 + 2048 + col];
;       p.out[(size_t)row * D + col] = xo + gt * v;
;     });
.LBB0_1517:
	v_subrev_u32_e32 v2, s0, v2
	v_and_or_b32 v2, v2, 40, v242
	ds_read_b64 v[2:3], v2
	v_lshlrev_b64 v[4:5], 12, v[30:31]
	v_lshlrev_b64 v[0:1], 12, v[0:1]
	v_lshl_add_u64 v[0:1], v[64:65], 0, v[0:1]
	s_mov_b64 s[2:3], 0
	s_waitcnt lgkmcnt(0)
	v_lshl_add_u64 v[2:3], v[2:3], 0, v[4:5]
	v_lshl_add_u64 v[2:3], v[162:163], 2, v[2:3]
	global_load_dword v4, v[2:3], off offset:128
	v_add_u32_e32 v2, v86, v118
	v_ashrrev_i32_e32 v3, 31, v2
	v_lshl_add_u64 v[2:3], v[2:3], 2, s[78:79]
	global_load_dword v2, v[2:3], off
	s_waitcnt vmcnt(0)
	v_fmac_f32_e32 v4, v15, v2
	global_store_dword v[0:1], v4, off offset:128

; __global__ void __launch_bounds__(256, 2) mega_kernel(Params p_arg) {
;   __shared__ __attribute__((aligned(16))) unsigned char smem[SMEM_BYTES];
;   const Params& p = *(const Params*)__builtin_amdgcn_kernarg_segment_ptr();
;   cg::grid_group grid = cg::this_grid();
;   __shared__ unsigned xbst[4];
	.amdhsa_kernel _Z11mega_kernel6Params
		.amdhsa_group_segment_fixed_size 74048
		.amdhsa_private_segment_fixed_size 0
		.amdhsa_kernarg_size 560
		.amdhsa_user_sgpr_count 2
		.amdhsa_user_sgpr_dispatch_ptr 0
		.amdhsa_user_sgpr_queue_ptr 0
		.amdhsa_user_sgpr_kernarg_segment_ptr 1
		.amdhsa_user_sgpr_dispatch_id 0
		.amdhsa_user_sgpr_kernarg_preload_length 0
		.amdhsa_user_sgpr_kernarg_preload_offset 0
		.amdhsa_user_sgpr_private_segment_size 0
		.amdhsa_uses_dynamic_stack 0
		.amdhsa_enable_private_segment 0
		.amdhsa_system_sgpr_workgroup_id_x 1
		.amdhsa_system_sgpr_workgroup_id_y 0
		.amdhsa_system_sgpr_workgroup_id_z 0
		.amdhsa_system_sgpr_workgroup_info 0
		.amdhsa_system_vgpr_workitem_id 2
		.amdhsa_next_free_vgpr 256
		.amdhsa_next_free_sgpr 100
		.amdhsa_accum_offset 256
		.amdhsa_reserve_vcc 1
		.amdhsa_float_round_mode_32 0
		.amdhsa_float_round_mode_16_64 0
		.amdhsa_float_denorm_mode_32 3
		.amdhsa_float_denorm_mode_16_64 3
		.amdhsa_dx10_clamp 1
		.amdhsa_ieee_mode 1
		.amdhsa_fp16_overflow 0
		.amdhsa_tg_split 0
		.amdhsa_exception_fp_ieee_invalid_op 0
		.amdhsa_exception_fp_denorm_src 0
		.amdhsa_exception_fp_ieee_div_zero 0
		.amdhsa_exception_fp_ieee_overflow 0
		.amdhsa_exception_fp_ieee_underflow 0
		.amdhsa_exception_fp_ieee_inexact 0
		.amdhsa_exception_int_div_zero 0
	.end_amdhsa_kernel

; __global__ void __launch_bounds__(256, 2) mega_kernel(Params p_arg) {
;   __shared__ __attribute__((aligned(16))) unsigned char smem[SMEM_BYTES];
;   const Params& p = *(const Params*)__builtin_amdgcn_kernarg_segment_ptr();
;   cg::grid_group grid = cg::this_grid();
;   __shared__ unsigned xbst[4];
amdhsa.kernels:
  - .agpr_count:     0
    .args:
      - .offset:         0
        .size:           304
        .value_kind:     by_value
      - .offset:         304
        .size:           4
        .value_kind:     hidden_block_count_x
      - .offset:         308
        .size:           4
        .value_kind:     hidden_block_count_y
      - .offset:         312
        .size:           4
        .value_kind:     hidden_block_count_z
      - .offset:         316
        .size:           2
        .value_kind:     hidden_group_size_x
      - .offset:         318
        .size:           2
        .value_kind:     hidden_group_size_y
      - .offset:         320
        .size:           2
        .value_kind:     hidden_group_size_z
      - .offset:         322
        .size:           2
        .value_kind:     hidden_remainder_x
      - .offset:         324
        .size:           2
        .value_kind:     hidden_remainder_y
      - .offset:         326
        .size:           2
        .value_kind:     hidden_remainder_z
      - .offset:         344
        .size:           8
        .value_kind:     hidden_global_offset_x
      - .offset:         352
        .size:           8
        .value_kind:     hidden_global_offset_y
      - .offset:         360
        .size:           8
        .value_kind:     hidden_global_offset_z
      - .offset:         368
        .size:           2
        .value_kind:     hidden_grid_dims
      - .offset:         392
        .size:           8
        .value_kind:     hidden_multigrid_sync_arg
    .group_segment_fixed_size: 74048
    .kernarg_segment_align: 8
    .kernarg_segment_size: 560
    .language:       OpenCL C
    .language_version:
      - 2
      - 0
    .max_flat_workgroup_size: 256
    .name:           _Z11mega_kernel6Params
    .private_segment_fixed_size: 0
    .sgpr_count:     106
    .sgpr_spill_count: 104
    .symbol:         _Z11mega_kernel6Params.kd
    .uniform_work_group_size: 1
    .uses_dynamic_stack: false
    .vgpr_count:     256
    .vgpr_spill_count: 0
    .wavefront_size: 64
